# GEMM K-loops: B-fragment-0 LDS reads moved out of the 12-read phases 1/5 into the read-free load segments 8/4 (covering vmcnt(10) one phase earlier, B0 re-read at each unit start)
# speedup vs baseline: 1.0453x; 1.0120x over previous
; #define PG8_STAGE(bufoff, gbase, voff) do { _Pragma("unroll") for (int _i = 0; _i < 2; ++_i) \
;         __builtin_amdgcn_global_load_lds((const unsigned*)((const char*)(gbase) + (voff)[_i]), (LAS unsigned*)(lds + (bufoff) + ldsw + _i * 8192), 16, 0, 0); } while (0)
; #define PG8_LDA(dst, b, h) do { _Pragma("unroll") for (int m = 0; m < 4; ++m) _Pragma("unroll") for (int k = 0; k < 2; ++k) dst[m][k] = *(const LAS bf16x8*)(lds + PG8_SA(b, h) + aoff + m * 2048 + k * 1024); } while (0)
; #define PG8_LDB(dst, b, h) do { _Pragma("unroll") for (int n = 0; n < 2; ++n) _Pragma("unroll") for (int k = 0; k < 2; ++k) dst[n][k] = *(const LAS bf16x8*)(lds + PG8_SB(b, h) + boff + n * 2048 + k * 1024); } while (0)
; #define PG8_WAIT_L(n) asm volatile("s_waitcnt lgkmcnt(" #n ")" ::: "memory")
; template <class Epi, class Sched, int LD>
; __device__ __forceinline__ void gemm_phase(LAS unsigned char* lds, const Gemm g, const Sched& S, const Epi& E) {
;     ...
;         const bool has_next = S.next(ui + 1, nxt);
;         const char* nA = has_next ? (const char*)g.A + (size_t)nxt.pm * tstep + (size_t)(nxt.kofs / BK) * kstep : cA; const char* nB = has_next ? (const char*)g.Bt + (size_t)nxt.pn * tstep + (size_t)(nxt.kofs / BK) * kstep : cB;
;         const int nt = cur.nt;
;         for (int t = 0; t < nt; t += 2) {
;             const bool last = (t == nt - 2);
;             const char* a1 = cA + (size_t)(t + 1) * kstep;
;             const char* a2 = last ? nA : cA + (size_t)(t + 2) * kstep; const char* b2 = last ? nB : cB + (size_t)(t + 2) * kstep;
;             const char* a3 = a2 + kstep; const char* b3 = b2 + kstep;
;             PG8_LDB(B0, 0, 0); PG8_SCHED; PG8_LDA(At, 0, 0); PG8_STAGE(PG8_SA(1, 1), a1 + hstep, voffA);
;             PG8_WAIT_L(8); PG8_BAR; PG8_WAIT_L(0); PG8_MMA(0, 0, At, B0); PG8_BAR; PG8_SCHED;
;             PG8_LDB(B1, 0, 1); PG8_STAGE(PG8_SB(0, 0), b2, voffB);
;             PG8_BAR; PG8_WAIT_L(0); PG8_MMA(0, 1, At, B1); PG8_BAR;
;             PG8_LDA(At, 0, 1); PG8_STAGE(PG8_SA(0, 0), a2, voffA);
;     ...
; #pragma unroll
;         for (int a = 0; a < 2; ++a)
; #pragma unroll
;             for (int b = 0; b < 2; ++b)
; #pragma unroll
;                 for (int m = 0; m < 4; ++m)
; #pragma unroll
;                     for (int n = 0; n < 2; ++n) acc[a][b][m][n] = (f32x4){0.f, 0.f, 0.f, 0.f};
;         cur = nxt; cA = nA; cB = nB; ++ui;
.LBB0_57:
	s_add_i32 s68, s65, -2
	s_add_u32 s46, s46, 0xc000
	s_addc_u32 s47, s47, 0
	s_add_u32 s69, s48, 0x10000
	v_mov_b32_e32 v4, 0
	s_addc_u32 s70, s49, 0
	s_mov_b32 s4, 0
	v_mov_b32_e32 v5, v4
	v_mov_b32_e32 v6, v4
	v_mov_b32_e32 v7, v4
	s_waitcnt vmcnt(0)
	v_mov_b32_e32 v8, v4
	v_mov_b32_e32 v9, v4
	v_mov_b32_e32 v10, v4
	v_mov_b32_e32 v11, v4
	v_mov_b32_e32 v20, v4
	v_mov_b32_e32 v21, v4
	v_mov_b32_e32 v22, v4
	v_mov_b32_e32 v23, v4
	v_mov_b32_e32 v24, v4
	v_mov_b32_e32 v25, v4
	v_mov_b32_e32 v26, v4
	v_mov_b32_e32 v27, v4
	v_mov_b32_e32 v36, v4
	v_mov_b32_e32 v37, v4
	v_mov_b32_e32 v38, v4
	v_mov_b32_e32 v39, v4
	v_mov_b32_e32 v40, v4
	v_mov_b32_e32 v41, v4
	v_mov_b32_e32 v42, v4
	v_mov_b32_e32 v43, v4
	v_mov_b32_e32 v52, v4
	v_mov_b32_e32 v53, v4
	v_mov_b32_e32 v54, v4
	v_mov_b32_e32 v55, v4
	v_mov_b32_e32 v56, v4
	v_mov_b32_e32 v57, v4
	v_mov_b32_e32 v58, v4
	v_mov_b32_e32 v59, v4
	v_mov_b32_e32 v12, v4
	v_mov_b32_e32 v13, v4
	v_mov_b32_e32 v14, v4
	v_mov_b32_e32 v15, v4
	v_mov_b32_e32 v16, v4
	v_mov_b32_e32 v17, v4
	v_mov_b32_e32 v18, v4
	v_mov_b32_e32 v19, v4
	v_mov_b32_e32 v28, v4
	v_mov_b32_e32 v29, v4
	v_mov_b32_e32 v30, v4
	v_mov_b32_e32 v31, v4
	v_mov_b32_e32 v32, v4
	v_mov_b32_e32 v33, v4
	v_mov_b32_e32 v34, v4
	v_mov_b32_e32 v35, v4
	v_mov_b32_e32 v44, v4
	v_mov_b32_e32 v45, v4
	v_mov_b32_e32 v46, v4
	v_mov_b32_e32 v47, v4
	v_mov_b32_e32 v48, v4
	v_mov_b32_e32 v49, v4
	v_mov_b32_e32 v50, v4
	v_mov_b32_e32 v51, v4
	v_mov_b32_e32 v60, v4
	v_mov_b32_e32 v61, v4
	v_mov_b32_e32 v62, v4
	v_mov_b32_e32 v63, v4
	v_mov_b32_e32 v64, v4
	v_mov_b32_e32 v65, v4
	v_mov_b32_e32 v66, v4
	v_mov_b32_e32 v67, v4
	v_mov_b32_e32 v68, v4
	v_mov_b32_e32 v69, v4
	v_mov_b32_e32 v70, v4
	v_mov_b32_e32 v71, v4
	v_mov_b32_e32 v72, v4
	v_mov_b32_e32 v73, v4
	v_mov_b32_e32 v74, v4
	v_mov_b32_e32 v75, v4
	v_mov_b32_e32 v84, v4
	v_mov_b32_e32 v85, v4
	v_mov_b32_e32 v86, v4
	v_mov_b32_e32 v87, v4
	v_mov_b32_e32 v88, v4
	v_mov_b32_e32 v89, v4
	v_mov_b32_e32 v90, v4
	v_mov_b32_e32 v91, v4
	v_mov_b32_e32 v100, v4
	v_mov_b32_e32 v101, v4
	v_mov_b32_e32 v102, v4
	v_mov_b32_e32 v103, v4
	v_mov_b32_e32 v104, v4
	v_mov_b32_e32 v105, v4
	v_mov_b32_e32 v106, v4
	v_mov_b32_e32 v107, v4
	v_mov_b32_e32 v116, v4
	v_mov_b32_e32 v117, v4
	v_mov_b32_e32 v118, v4
	v_mov_b32_e32 v119, v4
	v_mov_b32_e32 v120, v4
	v_mov_b32_e32 v121, v4
	v_mov_b32_e32 v122, v4
	v_mov_b32_e32 v123, v4
	v_mov_b32_e32 v76, v4
	v_mov_b32_e32 v77, v4
	v_mov_b32_e32 v78, v4
	v_mov_b32_e32 v79, v4
	v_mov_b32_e32 v80, v4
	v_mov_b32_e32 v81, v4
	v_mov_b32_e32 v82, v4
	v_mov_b32_e32 v83, v4
	v_mov_b32_e32 v92, v4
	v_mov_b32_e32 v93, v4
	v_mov_b32_e32 v94, v4
	v_mov_b32_e32 v95, v4
	v_mov_b32_e32 v96, v4
	v_mov_b32_e32 v97, v4
	v_mov_b32_e32 v98, v4
	v_mov_b32_e32 v99, v4
	v_mov_b32_e32 v108, v4
	v_mov_b32_e32 v109, v4
	v_mov_b32_e32 v110, v4
	v_mov_b32_e32 v111, v4
	v_mov_b32_e32 v112, v4
	v_mov_b32_e32 v113, v4
	v_mov_b32_e32 v114, v4
	v_mov_b32_e32 v115, v4
	v_mov_b32_e32 v124, v4
	v_mov_b32_e32 v125, v4
	v_mov_b32_e32 v126, v4
	v_mov_b32_e32 v127, v4
	v_mov_b32_e32 v128, v4
	v_mov_b32_e32 v129, v4
	v_mov_b32_e32 v130, v4
	v_mov_b32_e32 v131, v4
	ds_read_b128 v[140:143], v228
	ds_read_b128 v[150:153], v228 offset:1024
	ds_read_b128 v[154:157], v228 offset:2048
	ds_read_b128 v[176:179], v228 offset:3072
.LBB0_58:
	s_add_i32 s71, s4, 2
	s_add_u32 s48, s46, 0x4000
	s_addc_u32 s5, s47, 0
	s_cmp_eq_u32 s68, s4
	s_cselect_b32 s4, s42, s48
	s_cselect_b32 s5, s43, s5
	s_cselect_b32 s48, s44, s69
	s_cselect_b32 s49, s45, s70
	s_add_u32 s50, s4, 0x8000
	s_addc_u32 s51, s5, 0
	s_add_i32 s72, 0, 0x10000
	s_add_i32 m0, s39, 0xc000
	ds_read_b128 v[180:183], v148
	ds_read_b128 v[184:187], v148 offset:1024
	ds_read_b128 v[188:191], v148 offset:2048
	ds_read_b128 v[192:195], v148 offset:3072
	ds_read_b128 v[196:199], v148 offset:4096
	ds_read_b128 v[200:203], v148 offset:5120
	ds_read_b128 v[204:207], v148 offset:6144
	ds_read_b128 v[208:211], v148 offset:7168
	global_load_lds_dwordx4 v132, s[46:47]
	s_add_i32 m0, s39, 0xe000
	s_nop 0
	global_load_lds_dwordx4 v138, s[46:47]
	s_waitcnt lgkmcnt(8)
	s_barrier
	s_waitcnt lgkmcnt(0)
	s_setprio 0
	v_mfma_f32_16x16x32_bf16 v[128:131], v[140:143], v[180:183], v[128:131]
	v_mfma_f32_16x16x32_bf16 v[124:127], v[154:157], v[180:183], v[124:127]
	v_mfma_f32_16x16x32_bf16 v[112:115], v[140:143], v[188:191], v[112:115]
	v_mfma_f32_16x16x32_bf16 v[108:111], v[154:157], v[188:191], v[108:111]
	v_mfma_f32_16x16x32_bf16 v[96:99], v[140:143], v[196:199], v[96:99]
	v_mfma_f32_16x16x32_bf16 v[92:95], v[154:157], v[196:199], v[92:95]
	v_mfma_f32_16x16x32_bf16 v[80:83], v[140:143], v[204:207], v[80:83]
	v_mfma_f32_16x16x32_bf16 v[76:79], v[154:157], v[204:207], v[76:79]
	v_mfma_f32_16x16x32_bf16 v[128:131], v[150:153], v[184:187], v[128:131]
	v_mfma_f32_16x16x32_bf16 v[124:127], v[176:179], v[184:187], v[124:127]
	v_mfma_f32_16x16x32_bf16 v[112:115], v[150:153], v[192:195], v[112:115]
	v_mfma_f32_16x16x32_bf16 v[108:111], v[176:179], v[192:195], v[108:111]
	v_mfma_f32_16x16x32_bf16 v[96:99], v[150:153], v[200:203], v[96:99]
	v_mfma_f32_16x16x32_bf16 v[92:95], v[176:179], v[200:203], v[92:95]
	s_setprio 3
	s_barrier
	v_mfma_f32_16x16x32_bf16 v[80:83], v[150:153], v[208:211], v[80:83]
	v_mfma_f32_16x16x32_bf16 v[76:79], v[176:179], v[208:211], v[76:79]
	s_setprio 2
	s_add_i32 s74, 0, 0x14000
	s_add_i32 s72, s72, s29
	ds_read_b128 v[212:215], v228 offset:16384
	ds_read_b128 v[216:219], v228 offset:17408
	ds_read_b128 v[220:223], v228 offset:18432
	ds_read_b128 v[224:227], v228 offset:19456
	s_mov_b32 m0, s72
	s_nop 0
	global_load_lds_dwordx4 v132, s[48:49]
	s_add_i32 m0, s72, 0x2000
	s_nop 0
	global_load_lds_dwordx4 v138, s[48:49]
	s_barrier
; #define PG8_STAGE(bufoff, gbase, voff) do { _Pragma("unroll") for (int _i = 0; _i < 2; ++_i) \
;         __builtin_amdgcn_global_load_lds((const unsigned*)((const char*)(gbase) + (voff)[_i]), (LAS unsigned*)(lds + (bufoff) + ldsw + _i * 8192), 16, 0, 0); } while (0)
; #define PG8_LDA(dst, b, h) do { _Pragma("unroll") for (int m = 0; m < 4; ++m) _Pragma("unroll") for (int k = 0; k < 2; ++k) dst[m][k] = *(const LAS bf16x8*)(lds + PG8_SA(b, h) + aoff + m * 2048 + k * 1024); } while (0)
; #define PG8_LDB(dst, b, h) do { _Pragma("unroll") for (int n = 0; n < 2; ++n) _Pragma("unroll") for (int k = 0; k < 2; ++k) dst[n][k] = *(const LAS bf16x8*)(lds + PG8_SB(b, h) + boff + n * 2048 + k * 1024); } while (0)
; #define PG8_MMA(ai, bj, At, Bt) do { __builtin_amdgcn_s_setprio(1); _Pragma("unroll") for (int m = 0; m < 4; ++m) _Pragma("unroll") for (int n = 0; n < 2; ++n) _Pragma("unroll") for (int k = 0; k < 2; ++k) \
;         acc[ai][bj][m][n] = __builtin_amdgcn_mfma_f32_16x16x32_bf16(Bt[n][k], At[m][k], acc[ai][bj][m][n], 0, 0, 0); __builtin_amdgcn_s_setprio(0); } while (0)
; #define PG8_WAIT_V(n) asm volatile("s_waitcnt vmcnt(" #n ")" ::: "memory")
; #define PG8_WAIT_L(n) asm volatile("s_waitcnt lgkmcnt(" #n ")" ::: "memory")
; #define PG8_BAR __builtin_amdgcn_s_barrier()
; #define PG8_SCHED __builtin_amdgcn_sched_barrier(0)
; template <class Epi, class Sched, int LD>
; __device__ __forceinline__ void gemm_phase(LAS unsigned char* lds, const Gemm g, const Sched& S, const Epi& E) {
;     ...
;             PG8_BAR; PG8_WAIT_L(0); PG8_MMA(0, 1, At, B1); PG8_BAR;
;             PG8_LDA(At, 0, 1); PG8_STAGE(PG8_SA(0, 0), a2, voffA);
;             PG8_BAR; PG8_WAIT_L(0); PG8_MMA(1, 0, At, B0); PG8_BAR; PG8_SCHED;
;             PG8_STAGE(PG8_SB(0, 1), b2 + hstep, voffB);
;             PG8_WAIT_V(6); PG8_BAR; PG8_MMA(1, 1, At, B1); PG8_BAR;
;             PG8_LDB(B0, 1, 0); PG8_SCHED; PG8_LDA(At, 1, 0); PG8_STAGE(PG8_SA(0, 1), a2 + hstep, voffA);
;             PG8_WAIT_L(8); PG8_BAR; PG8_WAIT_L(0); PG8_MMA(0, 0, At, B0); PG8_BAR; PG8_SCHED;
	s_waitcnt lgkmcnt(0)
	s_setprio 0
	v_mfma_f32_16x16x32_bf16 v[120:123], v[212:215], v[180:183], v[120:123]
	v_mfma_f32_16x16x32_bf16 v[116:119], v[220:223], v[180:183], v[116:119]
	v_mfma_f32_16x16x32_bf16 v[104:107], v[212:215], v[188:191], v[104:107]
	v_mfma_f32_16x16x32_bf16 v[100:103], v[220:223], v[188:191], v[100:103]
	v_mfma_f32_16x16x32_bf16 v[88:91], v[212:215], v[196:199], v[88:91]
	v_mfma_f32_16x16x32_bf16 v[84:87], v[220:223], v[196:199], v[84:87]
	v_mfma_f32_16x16x32_bf16 v[72:75], v[212:215], v[204:207], v[72:75]
	v_mfma_f32_16x16x32_bf16 v[68:71], v[220:223], v[204:207], v[68:71]
	v_mfma_f32_16x16x32_bf16 v[120:123], v[216:219], v[184:187], v[120:123]
	v_mfma_f32_16x16x32_bf16 v[116:119], v[224:227], v[184:187], v[116:119]
	v_mfma_f32_16x16x32_bf16 v[104:107], v[216:219], v[192:195], v[104:107]
	v_mfma_f32_16x16x32_bf16 v[100:103], v[224:227], v[192:195], v[100:103]
	v_mfma_f32_16x16x32_bf16 v[88:91], v[216:219], v[200:203], v[88:91]
	v_mfma_f32_16x16x32_bf16 v[84:87], v[224:227], v[200:203], v[84:87]
	v_mfma_f32_16x16x32_bf16 v[72:75], v[216:219], v[208:211], v[72:75]
	v_mfma_f32_16x16x32_bf16 v[68:71], v[224:227], v[208:211], v[68:71]
	s_setprio 2
	s_mov_b32 m0, s39
	s_barrier
	ds_read_b128 v[180:183], v148 offset:16384
	ds_read_b128 v[184:187], v148 offset:17408
	ds_read_b128 v[188:191], v148 offset:18432
	ds_read_b128 v[192:195], v148 offset:19456
	ds_read_b128 v[196:199], v148 offset:20480
	ds_read_b128 v[200:203], v148 offset:21504
	ds_read_b128 v[204:207], v148 offset:22528
	ds_read_b128 v[208:211], v148 offset:23552
	global_load_lds_dwordx4 v132, s[4:5]
	s_mov_b32 m0, s52
	s_nop 0
	global_load_lds_dwordx4 v138, s[4:5]
	s_waitcnt vmcnt(10)
	s_barrier
	s_waitcnt lgkmcnt(0)
	s_setprio 0
	v_mfma_f32_16x16x32_bf16 v[64:67], v[140:143], v[180:183], v[64:67]
	v_mfma_f32_16x16x32_bf16 v[60:63], v[154:157], v[180:183], v[60:63]
	v_mfma_f32_16x16x32_bf16 v[48:51], v[140:143], v[188:191], v[48:51]
	v_mfma_f32_16x16x32_bf16 v[44:47], v[154:157], v[188:191], v[44:47]
	v_mfma_f32_16x16x32_bf16 v[32:35], v[140:143], v[196:199], v[32:35]
	v_mfma_f32_16x16x32_bf16 v[28:31], v[154:157], v[196:199], v[28:31]
	v_mfma_f32_16x16x32_bf16 v[16:19], v[140:143], v[204:207], v[16:19]
	v_mfma_f32_16x16x32_bf16 v[12:15], v[154:157], v[204:207], v[12:15]
	v_mfma_f32_16x16x32_bf16 v[64:67], v[150:153], v[184:187], v[64:67]
	v_mfma_f32_16x16x32_bf16 v[60:63], v[176:179], v[184:187], v[60:63]
	v_mfma_f32_16x16x32_bf16 v[48:51], v[150:153], v[192:195], v[48:51]
	v_mfma_f32_16x16x32_bf16 v[44:47], v[176:179], v[192:195], v[44:47]
	v_mfma_f32_16x16x32_bf16 v[32:35], v[150:153], v[200:203], v[32:35]
	v_mfma_f32_16x16x32_bf16 v[28:31], v[176:179], v[200:203], v[28:31]
	s_setprio 3
	s_barrier
	v_mfma_f32_16x16x32_bf16 v[16:19], v[150:153], v[208:211], v[16:19]
	v_mfma_f32_16x16x32_bf16 v[12:15], v[176:179], v[208:211], v[12:15]
	s_setprio 2
	ds_read_b128 v[140:143], v228 offset:32768
	ds_read_b128 v[150:153], v228 offset:33792
	ds_read_b128 v[154:157], v228 offset:34816
	ds_read_b128 v[176:179], v228 offset:35840
	s_add_u32 s72, s48, 0x4000
	s_addc_u32 s73, s49, 0
	s_add_i32 s74, s74, s29
	s_mov_b32 m0, s74
	s_nop 0
	global_load_lds_dwordx4 v132, s[72:73]
	s_add_i32 m0, s74, 0x2000
	s_nop 0
	global_load_lds_dwordx4 v138, s[72:73]
	s_waitcnt vmcnt(6)
	s_barrier
	s_setprio 0
	v_mfma_f32_16x16x32_bf16 v[56:59], v[212:215], v[180:183], v[56:59]
	v_mfma_f32_16x16x32_bf16 v[52:55], v[220:223], v[180:183], v[52:55]
	v_mfma_f32_16x16x32_bf16 v[40:43], v[212:215], v[188:191], v[40:43]
	v_mfma_f32_16x16x32_bf16 v[36:39], v[220:223], v[188:191], v[36:39]
	v_mfma_f32_16x16x32_bf16 v[24:27], v[212:215], v[196:199], v[24:27]
	v_mfma_f32_16x16x32_bf16 v[20:23], v[220:223], v[196:199], v[20:23]
	v_mfma_f32_16x16x32_bf16 v[8:11], v[212:215], v[204:207], v[8:11]
	v_mfma_f32_16x16x32_bf16 v[4:7], v[220:223], v[204:207], v[4:7]
	v_mfma_f32_16x16x32_bf16 v[56:59], v[216:219], v[184:187], v[56:59]
	v_mfma_f32_16x16x32_bf16 v[52:55], v[224:227], v[184:187], v[52:55]
	v_mfma_f32_16x16x32_bf16 v[40:43], v[216:219], v[192:195], v[40:43]
	v_mfma_f32_16x16x32_bf16 v[36:39], v[224:227], v[192:195], v[36:39]
	v_mfma_f32_16x16x32_bf16 v[24:27], v[216:219], v[200:203], v[24:27]
	v_mfma_f32_16x16x32_bf16 v[20:23], v[224:227], v[200:203], v[20:23]
	v_mfma_f32_16x16x32_bf16 v[8:11], v[216:219], v[208:211], v[8:11]
	v_mfma_f32_16x16x32_bf16 v[4:7], v[224:227], v[208:211], v[4:7]
	s_setprio 2
	s_add_i32 s72, 0, 0x18000
	s_barrier
	s_add_u32 s4, s4, 0x4000
	s_addc_u32 s5, s5, 0
	s_mov_b32 m0, s53
	ds_read_b128 v[180:183], v148 offset:32768
	ds_read_b128 v[184:187], v148 offset:33792
	ds_read_b128 v[188:191], v148 offset:34816
	ds_read_b128 v[192:195], v148 offset:35840
	ds_read_b128 v[196:199], v148 offset:36864
	ds_read_b128 v[200:203], v148 offset:37888
	ds_read_b128 v[204:207], v148 offset:38912
	ds_read_b128 v[208:211], v148 offset:39936
	global_load_lds_dwordx4 v132, s[4:5]
	s_mov_b32 m0, s54
	s_nop 0
	global_load_lds_dwordx4 v138, s[4:5]
	s_waitcnt lgkmcnt(8)
	s_barrier
	s_waitcnt lgkmcnt(0)
	s_setprio 0
	v_mfma_f32_16x16x32_bf16 v[128:131], v[140:143], v[180:183], v[128:131]
	v_mfma_f32_16x16x32_bf16 v[124:127], v[154:157], v[180:183], v[124:127]
	v_mfma_f32_16x16x32_bf16 v[112:115], v[140:143], v[188:191], v[112:115]
	v_mfma_f32_16x16x32_bf16 v[108:111], v[154:157], v[188:191], v[108:111]
	v_mfma_f32_16x16x32_bf16 v[96:99], v[140:143], v[196:199], v[96:99]
	v_mfma_f32_16x16x32_bf16 v[92:95], v[154:157], v[196:199], v[92:95]
	v_mfma_f32_16x16x32_bf16 v[80:83], v[140:143], v[204:207], v[80:83]
	v_mfma_f32_16x16x32_bf16 v[76:79], v[154:157], v[204:207], v[76:79]
	v_mfma_f32_16x16x32_bf16 v[128:131], v[150:153], v[184:187], v[128:131]
	v_mfma_f32_16x16x32_bf16 v[124:127], v[176:179], v[184:187], v[124:127]
	v_mfma_f32_16x16x32_bf16 v[112:115], v[150:153], v[192:195], v[112:115]
	v_mfma_f32_16x16x32_bf16 v[108:111], v[176:179], v[192:195], v[108:111]
	v_mfma_f32_16x16x32_bf16 v[96:99], v[150:153], v[200:203], v[96:99]
	v_mfma_f32_16x16x32_bf16 v[92:95], v[176:179], v[200:203], v[92:95]
	s_setprio 3
	s_barrier
; #define PG8_STAGE(bufoff, gbase, voff) do { _Pragma("unroll") for (int _i = 0; _i < 2; ++_i) \
;         __builtin_amdgcn_global_load_lds((const unsigned*)((const char*)(gbase) + (voff)[_i]), (LAS unsigned*)(lds + (bufoff) + ldsw + _i * 8192), 16, 0, 0); } while (0)
; #define PG8_LDA(dst, b, h) do { _Pragma("unroll") for (int m = 0; m < 4; ++m) _Pragma("unroll") for (int k = 0; k < 2; ++k) dst[m][k] = *(const LAS bf16x8*)(lds + PG8_SA(b, h) + aoff + m * 2048 + k * 1024); } while (0)
; #define PG8_LDB(dst, b, h) do { _Pragma("unroll") for (int n = 0; n < 2; ++n) _Pragma("unroll") for (int k = 0; k < 2; ++k) dst[n][k] = *(const LAS bf16x8*)(lds + PG8_SB(b, h) + boff + n * 2048 + k * 1024); } while (0)
; #define PG8_MMA(ai, bj, At, Bt) do { __builtin_amdgcn_s_setprio(1); _Pragma("unroll") for (int m = 0; m < 4; ++m) _Pragma("unroll") for (int n = 0; n < 2; ++n) _Pragma("unroll") for (int k = 0; k < 2; ++k) \
;         acc[ai][bj][m][n] = __builtin_amdgcn_mfma_f32_16x16x32_bf16(Bt[n][k], At[m][k], acc[ai][bj][m][n], 0, 0, 0); __builtin_amdgcn_s_setprio(0); } while (0)
; #define PG8_WAIT_V(n) asm volatile("s_waitcnt vmcnt(" #n ")" ::: "memory")
; #define PG8_WAIT_L(n) asm volatile("s_waitcnt lgkmcnt(" #n ")" ::: "memory")
; #define PG8_BAR __builtin_amdgcn_s_barrier()
; #define PG8_SCHED __builtin_amdgcn_sched_barrier(0)
; template <class Epi, class Sched, int LD>
; __device__ __forceinline__ void gemm_phase(LAS unsigned char* lds, const Gemm g, const Sched& S, const Epi& E) {
;     ...
;             PG8_WAIT_L(8); PG8_BAR; PG8_WAIT_L(0); PG8_MMA(0, 0, At, B0); PG8_BAR; PG8_SCHED;
;             PG8_LDB(B1, 1, 1); PG8_STAGE(PG8_SB(1, 0), b3, voffB);
;             PG8_BAR; PG8_WAIT_L(0); PG8_MMA(0, 1, At, B1); PG8_BAR;
;             PG8_LDA(At, 1, 1); PG8_STAGE(PG8_SA(1, 0), a3, voffA);
;             PG8_BAR; PG8_WAIT_L(0); PG8_MMA(1, 0, At, B0); PG8_BAR; PG8_SCHED;
;             PG8_STAGE(PG8_SB(1, 1), b3 + hstep, voffB);
;             PG8_WAIT_V(6); PG8_BAR; PG8_MMA(1, 1, At, B1); PG8_BAR;
	v_mfma_f32_16x16x32_bf16 v[80:83], v[150:153], v[208:211], v[80:83]
	v_mfma_f32_16x16x32_bf16 v[76:79], v[176:179], v[208:211], v[76:79]
	s_setprio 2
	s_add_i32 s73, 0, 0x1c000
	s_add_u32 s4, s48, 0x8000
	s_addc_u32 s5, s49, 0
	s_add_i32 s72, s72, s29
	ds_read_b128 v[212:215], v228 offset:49152
	ds_read_b128 v[216:219], v228 offset:50176
	ds_read_b128 v[220:223], v228 offset:51200
	ds_read_b128 v[224:227], v228 offset:52224
	s_mov_b32 m0, s72
	s_nop 0
	global_load_lds_dwordx4 v132, s[4:5]
	s_add_i32 m0, s72, 0x2000
	s_nop 0
	global_load_lds_dwordx4 v138, s[4:5]
	s_barrier
	s_waitcnt lgkmcnt(0)
	s_setprio 0
	v_mfma_f32_16x16x32_bf16 v[120:123], v[212:215], v[180:183], v[120:123]
	v_mfma_f32_16x16x32_bf16 v[116:119], v[220:223], v[180:183], v[116:119]
	v_mfma_f32_16x16x32_bf16 v[104:107], v[212:215], v[188:191], v[104:107]
	v_mfma_f32_16x16x32_bf16 v[100:103], v[220:223], v[188:191], v[100:103]
	v_mfma_f32_16x16x32_bf16 v[88:91], v[212:215], v[196:199], v[88:91]
	v_mfma_f32_16x16x32_bf16 v[84:87], v[220:223], v[196:199], v[84:87]
	v_mfma_f32_16x16x32_bf16 v[72:75], v[212:215], v[204:207], v[72:75]
	v_mfma_f32_16x16x32_bf16 v[68:71], v[220:223], v[204:207], v[68:71]
	v_mfma_f32_16x16x32_bf16 v[120:123], v[216:219], v[184:187], v[120:123]
	v_mfma_f32_16x16x32_bf16 v[116:119], v[224:227], v[184:187], v[116:119]
	v_mfma_f32_16x16x32_bf16 v[104:107], v[216:219], v[192:195], v[104:107]
	v_mfma_f32_16x16x32_bf16 v[100:103], v[224:227], v[192:195], v[100:103]
	v_mfma_f32_16x16x32_bf16 v[88:91], v[216:219], v[200:203], v[88:91]
	v_mfma_f32_16x16x32_bf16 v[84:87], v[224:227], v[200:203], v[84:87]
	v_mfma_f32_16x16x32_bf16 v[72:75], v[216:219], v[208:211], v[72:75]
	v_mfma_f32_16x16x32_bf16 v[68:71], v[224:227], v[208:211], v[68:71]
	s_setprio 2
	s_mov_b32 m0, s55
	s_barrier
	ds_read_b128 v[180:183], v148 offset:49152
	ds_read_b128 v[184:187], v148 offset:50176
	ds_read_b128 v[188:191], v148 offset:51200
	ds_read_b128 v[192:195], v148 offset:52224
	ds_read_b128 v[196:199], v148 offset:53248
	ds_read_b128 v[200:203], v148 offset:54272
	ds_read_b128 v[204:207], v148 offset:55296
	ds_read_b128 v[208:211], v148 offset:56320
	global_load_lds_dwordx4 v132, s[50:51]
	s_mov_b32 m0, s56
	s_nop 0
	global_load_lds_dwordx4 v138, s[50:51]
	s_waitcnt vmcnt(10)
	s_barrier
	s_waitcnt lgkmcnt(0)
	s_setprio 0
	v_mfma_f32_16x16x32_bf16 v[64:67], v[140:143], v[180:183], v[64:67]
	v_mfma_f32_16x16x32_bf16 v[60:63], v[154:157], v[180:183], v[60:63]
	v_mfma_f32_16x16x32_bf16 v[48:51], v[140:143], v[188:191], v[48:51]
	v_mfma_f32_16x16x32_bf16 v[44:47], v[154:157], v[188:191], v[44:47]
	v_mfma_f32_16x16x32_bf16 v[32:35], v[140:143], v[196:199], v[32:35]
	v_mfma_f32_16x16x32_bf16 v[28:31], v[154:157], v[196:199], v[28:31]
	v_mfma_f32_16x16x32_bf16 v[16:19], v[140:143], v[204:207], v[16:19]
	v_mfma_f32_16x16x32_bf16 v[12:15], v[154:157], v[204:207], v[12:15]
	v_mfma_f32_16x16x32_bf16 v[64:67], v[150:153], v[184:187], v[64:67]
	v_mfma_f32_16x16x32_bf16 v[60:63], v[176:179], v[184:187], v[60:63]
	v_mfma_f32_16x16x32_bf16 v[48:51], v[150:153], v[192:195], v[48:51]
	v_mfma_f32_16x16x32_bf16 v[44:47], v[176:179], v[192:195], v[44:47]
	v_mfma_f32_16x16x32_bf16 v[32:35], v[150:153], v[200:203], v[32:35]
	v_mfma_f32_16x16x32_bf16 v[28:31], v[176:179], v[200:203], v[28:31]
	s_setprio 3
	s_barrier
	v_mfma_f32_16x16x32_bf16 v[16:19], v[150:153], v[208:211], v[16:19]
	v_mfma_f32_16x16x32_bf16 v[12:15], v[176:179], v[208:211], v[12:15]
	s_setprio 2
	ds_read_b128 v[140:143], v228
	ds_read_b128 v[150:153], v228 offset:1024
	ds_read_b128 v[154:157], v228 offset:2048
	ds_read_b128 v[176:179], v228 offset:3072
	s_add_u32 s4, s48, 0xc000
	s_addc_u32 s5, s49, 0
	s_add_i32 s48, s73, s29
	s_mov_b32 m0, s48
	s_nop 0
	global_load_lds_dwordx4 v132, s[4:5]
	s_add_i32 m0, s48, 0x2000
	s_nop 0
	global_load_lds_dwordx4 v138, s[4:5]
	s_waitcnt vmcnt(6)
	s_barrier
	s_setprio 0
	v_mfma_f32_16x16x32_bf16 v[56:59], v[212:215], v[180:183], v[56:59]
	v_mfma_f32_16x16x32_bf16 v[52:55], v[220:223], v[180:183], v[52:55]
	v_mfma_f32_16x16x32_bf16 v[40:43], v[212:215], v[188:191], v[40:43]
	v_mfma_f32_16x16x32_bf16 v[36:39], v[220:223], v[188:191], v[36:39]
	v_mfma_f32_16x16x32_bf16 v[24:27], v[212:215], v[196:199], v[24:27]
	v_mfma_f32_16x16x32_bf16 v[20:23], v[220:223], v[196:199], v[20:23]
	v_mfma_f32_16x16x32_bf16 v[8:11], v[212:215], v[204:207], v[8:11]
	v_mfma_f32_16x16x32_bf16 v[4:7], v[220:223], v[204:207], v[4:7]
	v_mfma_f32_16x16x32_bf16 v[56:59], v[216:219], v[184:187], v[56:59]
	v_mfma_f32_16x16x32_bf16 v[52:55], v[224:227], v[184:187], v[52:55]
	v_mfma_f32_16x16x32_bf16 v[40:43], v[216:219], v[192:195], v[40:43]
	v_mfma_f32_16x16x32_bf16 v[36:39], v[224:227], v[192:195], v[36:39]
	v_mfma_f32_16x16x32_bf16 v[24:27], v[216:219], v[200:203], v[24:27]
	v_mfma_f32_16x16x32_bf16 v[20:23], v[224:227], v[200:203], v[20:23]
	v_mfma_f32_16x16x32_bf16 v[8:11], v[216:219], v[208:211], v[8:11]
	v_mfma_f32_16x16x32_bf16 v[4:7], v[224:227], v[208:211], v[4:7]
	s_setprio 2
	s_add_u32 s46, s46, 0x10000
	s_addc_u32 s47, s47, 0
	s_add_u32 s69, s69, 0x10000
	s_addc_u32 s70, s70, 0
	s_cmp_ge_i32 s71, s65
	s_mov_b32 s4, s71
	s_barrier
;     __device__ __forceinline__ void operator()(const f32x4 (&acc)[2][2][4][2], const Unit& u, int wr, int wc, int fr, int fq) const {
;     ...
;             float* base = PART + (size_t)u.part * (512 * 2048);
; #pragma unroll
;             for (int ai = 0; ai < 2; ++ai)
; #pragma unroll
;                 for (int m = 0; m < 4; ++m) {
;                     float* rowp = base + (size_t)(row0 - 8192 + ai * HALF + m * 16) * D_MODEL + col0;
; #pragma unroll
;                     for (int bj = 0; bj < 2; ++bj)
; #pragma unroll
;                         for (int n = 0; n < 2; ++n) *(f32x4*)(rowp + bj * HALF + n * 16) = acc[ai][bj][m][n];
;                 }
; template <class Epi, class Sched, int LD>
; __device__ __forceinline__ void gemm_phase(LAS unsigned char* lds, const Gemm g, const Sched& S, const Epi& E) {
;     ...
;         }
;         E(acc, cur, wr, wc, fr, fq);
	s_cbranch_scc0 .LBB0_58
	s_setprio 0
	v_lshl_add_u32 v142, s67, 8, v137
	v_lshl_or_b32 v140, s66, 8, v147
	s_mov_b64 s[4:5], -1
	s_cmp_gt_i32 s18, -1
	v_ashrrev_i32_e32 v141, 31, v140
	v_ashrrev_i32_e32 v143, 31, v142
	s_cbranch_scc0 .LBB0_61
	s_lshl_b64 s[4:5], s[18:19], 22
	v_readlane_b32 s18, v252, 10
	s_add_u32 s4, s18, s4
	v_readlane_b32 s18, v252, 11
	s_addc_u32 s5, s18, s5
	v_lshl_add_u64 v[144:145], v[140:141], 2, s[4:5]
	v_lshlrev_b64 v[150:151], 13, v[142:143]
	s_brev_b32 s4, 63
	v_lshl_add_u64 v[144:145], v[144:145], 0, v[150:151]
	s_mov_b32 s5, -1
	v_lshl_add_u64 v[150:151], v[144:145], 0, s[4:5]
	s_brev_b32 s4, 63
	v_add_co_u32_e32 v152, vcc, s4, v144
	s_mov_b32 s4, 0xfc020000
	s_nop 0
	v_addc_co_u32_e32 v153, vcc, -1, v145, vcc
	s_mov_b32 s5, -1
	global_store_dwordx4 v[152:153], v[128:131], off
	global_store_dwordx4 v[150:151], v[124:127], off offset:64
	global_store_dwordx4 v[150:151], v[120:123], off offset:512
	global_store_dwordx4 v[150:151], v[116:119], off offset:576
	v_lshl_add_u64 v[150:151], v[144:145], 0, s[4:5]
	s_mov_b32 s4, 0xfc020000
	v_add_co_u32_e32 v152, vcc, s4, v144
	s_mov_b32 s4, 0xfc040000
	s_nop 0
	v_addc_co_u32_e32 v153, vcc, -1, v145, vcc
	s_mov_b32 s5, -1
	global_store_dwordx4 v[152:153], v[112:115], off
	global_store_dwordx4 v[150:151], v[108:111], off offset:64
	global_store_dwordx4 v[150:151], v[104:107], off offset:512
	global_store_dwordx4 v[150:151], v[100:103], off offset:576
	v_lshl_add_u64 v[150:151], v[144:145], 0, s[4:5]
	s_mov_b32 s4, 0xfc040000
	v_add_co_u32_e32 v152, vcc, s4, v144
	s_mov_b32 s4, 0xfc060000
	s_nop 0
	v_addc_co_u32_e32 v153, vcc, -1, v145, vcc
	s_mov_b32 s5, -1
	global_store_dwordx4 v[152:153], v[96:99], off
	global_store_dwordx4 v[150:151], v[92:95], off offset:64
	global_store_dwordx4 v[150:151], v[88:91], off offset:512
	global_store_dwordx4 v[150:151], v[84:87], off offset:576
	v_lshl_add_u64 v[150:151], v[144:145], 0, s[4:5]
	s_mov_b32 s4, 0xfc060000
	v_add_co_u32_e32 v152, vcc, s4, v144
	s_mov_b32 s4, 0xfc100000
	s_nop 0
	v_addc_co_u32_e32 v153, vcc, -1, v145, vcc
	s_mov_b32 s5, -1
	global_store_dwordx4 v[152:153], v[80:83], off
	global_store_dwordx4 v[150:151], v[76:79], off offset:64
	global_store_dwordx4 v[150:151], v[72:75], off offset:512
	global_store_dwordx4 v[150:151], v[68:71], off offset:576
	v_lshl_add_u64 v[150:151], v[144:145], 0, s[4:5]
	s_mov_b32 s4, 0xfc100000
	v_add_co_u32_e32 v152, vcc, s4, v144
	s_mov_b32 s4, 0xfc120000
	s_nop 0
	v_addc_co_u32_e32 v153, vcc, -1, v145, vcc
	s_mov_b32 s5, -1
	global_store_dwordx4 v[152:153], v[64:67], off
	global_store_dwordx4 v[150:151], v[60:63], off offset:64
	global_store_dwordx4 v[150:151], v[56:59], off offset:512
	global_store_dwordx4 v[150:151], v[52:55], off offset:576
	v_lshl_add_u64 v[150:151], v[144:145], 0, s[4:5]
	s_mov_b32 s4, 0xfc120000
	v_add_co_u32_e32 v152, vcc, s4, v144
	s_mov_b32 s4, 0xfc140000
	s_nop 0
	v_addc_co_u32_e32 v153, vcc, -1, v145, vcc
	s_mov_b32 s5, -1
	global_store_dwordx4 v[152:153], v[48:51], off
	global_store_dwordx4 v[150:151], v[44:47], off offset:64
	global_store_dwordx4 v[150:151], v[40:43], off offset:512
	global_store_dwordx4 v[150:151], v[36:39], off offset:576
	v_lshl_add_u64 v[150:151], v[144:145], 0, s[4:5]
	s_mov_b32 s4, 0xfc140000
	v_add_co_u32_e32 v152, vcc, s4, v144
	s_mov_b32 s4, 0xfc160000
	s_nop 0
	v_addc_co_u32_e32 v153, vcc, -1, v145, vcc
	s_mov_b32 s5, -1
	global_store_dwordx4 v[152:153], v[32:35], off
	global_store_dwordx4 v[150:151], v[28:31], off offset:64
	global_store_dwordx4 v[150:151], v[24:27], off offset:512
	global_store_dwordx4 v[150:151], v[20:23], off offset:576
	v_lshl_add_u64 v[150:151], v[144:145], 0, s[4:5]
	v_add_co_u32_e32 v144, vcc, 0xfc160000, v144
	s_mov_b64 s[4:5], 0
	s_nop 0
	v_addc_co_u32_e32 v145, vcc, -1, v145, vcc
	global_store_dwordx4 v[144:145], v[16:19], off
	global_store_dwordx4 v[150:151], v[12:15], off offset:64
	global_store_dwordx4 v[150:151], v[8:11], off offset:512
	global_store_dwordx4 v[150:151], v[4:7], off offset:576

; #define PG8_STAGE(bufoff, gbase, voff) do { _Pragma("unroll") for (int _i = 0; _i < 2; ++_i) \
;         __builtin_amdgcn_global_load_lds((const unsigned*)((const char*)(gbase) + (voff)[_i]), (LAS unsigned*)(lds + (bufoff) + ldsw + _i * 8192), 16, 0, 0); } while (0)
; #define PG8_LDA(dst, b, h) do { _Pragma("unroll") for (int m = 0; m < 4; ++m) _Pragma("unroll") for (int k = 0; k < 2; ++k) dst[m][k] = *(const LAS bf16x8*)(lds + PG8_SA(b, h) + aoff + m * 2048 + k * 1024); } while (0)
; #define PG8_LDB(dst, b, h) do { _Pragma("unroll") for (int n = 0; n < 2; ++n) _Pragma("unroll") for (int k = 0; k < 2; ++k) dst[n][k] = *(const LAS bf16x8*)(lds + PG8_SB(b, h) + boff + n * 2048 + k * 1024); } while (0)
; #define PG8_WAIT_L(n) asm volatile("s_waitcnt lgkmcnt(" #n ")" ::: "memory")
; template <class Epi, class Sched, int LD>
; __device__ __forceinline__ void gemm_phase(LAS unsigned char* lds, const Gemm g, const Sched& S, const Epi& E) {
;     ...
;         const bool has_next = S.next(ui + 1, nxt);
;         const char* nA = has_next ? (const char*)g.A + (size_t)nxt.pm * tstep + (size_t)(nxt.kofs / BK) * kstep : cA; const char* nB = has_next ? (const char*)g.Bt + (size_t)nxt.pn * tstep + (size_t)(nxt.kofs / BK) * kstep : cB;
;         const int nt = cur.nt;
;         for (int t = 0; t < nt; t += 2) {
;             const bool last = (t == nt - 2);
;             const char* a1 = cA + (size_t)(t + 1) * kstep;
;             const char* a2 = last ? nA : cA + (size_t)(t + 2) * kstep; const char* b2 = last ? nB : cB + (size_t)(t + 2) * kstep;
;             const char* a3 = a2 + kstep; const char* b3 = b2 + kstep;
;             PG8_LDB(B0, 0, 0); PG8_SCHED; PG8_LDA(At, 0, 0); PG8_STAGE(PG8_SA(1, 1), a1 + hstep, voffA);
;             PG8_WAIT_L(8); PG8_BAR; PG8_WAIT_L(0); PG8_MMA(0, 0, At, B0); PG8_BAR; PG8_SCHED;
;             PG8_LDB(B1, 0, 1); PG8_STAGE(PG8_SB(0, 0), b2, voffB);
;             PG8_BAR; PG8_WAIT_L(0); PG8_MMA(0, 1, At, B1); PG8_BAR;
;             PG8_LDA(At, 0, 1); PG8_STAGE(PG8_SA(0, 0), a2, voffA);
;     ...
; #pragma unroll
;         for (int a = 0; a < 2; ++a)
; #pragma unroll
;             for (int b = 0; b < 2; ++b)
; #pragma unroll
;                 for (int m = 0; m < 4; ++m)
; #pragma unroll
;                     for (int n = 0; n < 2; ++n) acc[a][b][m][n] = (f32x4){0.f, 0.f, 0.f, 0.f};
;         cur = nxt; cA = nA; cB = nB; ++ui;
.LBB0_500:
	s_add_u32 s54, s4, 0xc000
	s_addc_u32 s55, s5, 0
	s_add_u32 s29, s56, 0x10000
	v_mov_b32_e32 v4, 0
	s_addc_u32 s47, s57, 0
	s_mov_b32 s49, -2
	v_mov_b32_e32 v5, v4
	v_mov_b32_e32 v6, v4
	v_mov_b32_e32 v7, v4
	v_mov_b32_e32 v8, v4
	v_mov_b32_e32 v9, v4
	v_mov_b32_e32 v10, v4
	v_mov_b32_e32 v11, v4
	v_mov_b32_e32 v12, v4
	v_mov_b32_e32 v13, v4
	v_mov_b32_e32 v14, v4
	v_mov_b32_e32 v15, v4
	v_mov_b32_e32 v16, v4
	v_mov_b32_e32 v17, v4
	v_mov_b32_e32 v18, v4
	v_mov_b32_e32 v19, v4
	v_mov_b32_e32 v28, v4
	v_mov_b32_e32 v29, v4
	v_mov_b32_e32 v30, v4
	v_mov_b32_e32 v31, v4
	v_mov_b32_e32 v32, v4
	v_mov_b32_e32 v33, v4
	v_mov_b32_e32 v34, v4
	v_mov_b32_e32 v35, v4
	v_mov_b32_e32 v44, v4
	v_mov_b32_e32 v45, v4
	v_mov_b32_e32 v46, v4
	v_mov_b32_e32 v47, v4
	v_mov_b32_e32 v48, v4
	v_mov_b32_e32 v49, v4
	v_mov_b32_e32 v50, v4
	v_mov_b32_e32 v51, v4
	v_mov_b32_e32 v20, v4
	v_mov_b32_e32 v21, v4
	v_mov_b32_e32 v22, v4
	v_mov_b32_e32 v23, v4
	v_mov_b32_e32 v24, v4
	v_mov_b32_e32 v25, v4
	v_mov_b32_e32 v26, v4
	v_mov_b32_e32 v27, v4
	v_mov_b32_e32 v36, v4
	v_mov_b32_e32 v37, v4
	v_mov_b32_e32 v38, v4
	v_mov_b32_e32 v39, v4
	v_mov_b32_e32 v40, v4
	v_mov_b32_e32 v41, v4
	v_mov_b32_e32 v42, v4
	v_mov_b32_e32 v43, v4
	v_mov_b32_e32 v52, v4
	v_mov_b32_e32 v53, v4
	v_mov_b32_e32 v54, v4
	v_mov_b32_e32 v55, v4
	v_mov_b32_e32 v56, v4
	v_mov_b32_e32 v57, v4
	v_mov_b32_e32 v58, v4
	v_mov_b32_e32 v59, v4
	v_mov_b32_e32 v60, v4
	v_mov_b32_e32 v61, v4
	v_mov_b32_e32 v62, v4
	v_mov_b32_e32 v63, v4
	v_mov_b32_e32 v64, v4
	v_mov_b32_e32 v65, v4
	v_mov_b32_e32 v66, v4
	v_mov_b32_e32 v67, v4
	v_mov_b32_e32 v68, v4
	v_mov_b32_e32 v69, v4
	v_mov_b32_e32 v70, v4
	v_mov_b32_e32 v71, v4
	v_mov_b32_e32 v72, v4
	v_mov_b32_e32 v73, v4
	v_mov_b32_e32 v74, v4
	v_mov_b32_e32 v75, v4
	v_mov_b32_e32 v76, v4
	v_mov_b32_e32 v77, v4
	v_mov_b32_e32 v78, v4
	v_mov_b32_e32 v79, v4
	v_mov_b32_e32 v80, v4
	v_mov_b32_e32 v81, v4
	v_mov_b32_e32 v82, v4
	v_mov_b32_e32 v83, v4
	v_mov_b32_e32 v92, v4
	v_mov_b32_e32 v93, v4
	v_mov_b32_e32 v94, v4
	v_mov_b32_e32 v95, v4
	v_mov_b32_e32 v96, v4
	v_mov_b32_e32 v97, v4
	v_mov_b32_e32 v98, v4
	v_mov_b32_e32 v99, v4
	v_mov_b32_e32 v108, v4
	v_mov_b32_e32 v109, v4
	v_mov_b32_e32 v110, v4
	v_mov_b32_e32 v111, v4
	v_mov_b32_e32 v112, v4
	v_mov_b32_e32 v113, v4
	v_mov_b32_e32 v114, v4
	v_mov_b32_e32 v115, v4
	v_mov_b32_e32 v84, v4
	v_mov_b32_e32 v85, v4
	v_mov_b32_e32 v86, v4
	v_mov_b32_e32 v87, v4
	v_mov_b32_e32 v88, v4
	v_mov_b32_e32 v89, v4
	v_mov_b32_e32 v90, v4
	v_mov_b32_e32 v91, v4
	v_mov_b32_e32 v100, v4
	v_mov_b32_e32 v101, v4
	v_mov_b32_e32 v102, v4
	v_mov_b32_e32 v103, v4
	v_mov_b32_e32 v104, v4
	v_mov_b32_e32 v105, v4
	v_mov_b32_e32 v106, v4
	v_mov_b32_e32 v107, v4
	v_mov_b32_e32 v116, v4
	v_mov_b32_e32 v117, v4
	v_mov_b32_e32 v118, v4
	v_mov_b32_e32 v119, v4
	v_mov_b32_e32 v120, v4
	v_mov_b32_e32 v121, v4
	v_mov_b32_e32 v122, v4
	v_mov_b32_e32 v123, v4
	v_mov_b32_e32 v124, v4
	v_mov_b32_e32 v125, v4
	v_mov_b32_e32 v126, v4
	v_mov_b32_e32 v127, v4
	v_mov_b32_e32 v128, v4
	v_mov_b32_e32 v129, v4
	v_mov_b32_e32 v130, v4
	v_mov_b32_e32 v131, v4
	ds_read_b128 v[148:151], v228
	ds_read_b128 v[152:155], v228 offset:1024
	ds_read_b128 v[156:159], v228 offset:2048
	ds_read_b128 v[176:179], v228 offset:3072
.LBB0_501:
	s_add_u32 s4, s54, 0x4000
	s_addc_u32 s5, s55, 0
	s_cmp_eq_u32 s49, 28
	s_cselect_b32 s4, s50, s4
	s_cselect_b32 s5, s51, s5
	s_cselect_b32 s56, s40, s29
	s_cselect_b32 s57, s41, s47
	s_add_u32 s58, s4, 0x8000
	s_addc_u32 s59, s5, 0
	s_add_i32 s69, 0, 0x10000
	s_add_i32 m0, s52, 0xc000
	ds_read_b128 v[180:183], v146
	ds_read_b128 v[184:187], v146 offset:1024
	ds_read_b128 v[188:191], v146 offset:2048
	ds_read_b128 v[192:195], v146 offset:3072
	ds_read_b128 v[196:199], v146 offset:4096
	ds_read_b128 v[200:203], v146 offset:5120
	ds_read_b128 v[204:207], v146 offset:6144
	ds_read_b128 v[208:211], v146 offset:7168
	global_load_lds_dwordx4 v132, s[54:55]
	s_add_i32 m0, s52, 0xe000
	s_nop 0
	global_load_lds_dwordx4 v138, s[54:55]
	s_waitcnt lgkmcnt(8)
	s_barrier
	s_waitcnt lgkmcnt(0)
	s_setprio 0
	v_mfma_f32_16x16x32_bf16 v[128:131], v[148:151], v[180:183], v[128:131]
	v_mfma_f32_16x16x32_bf16 v[124:127], v[156:159], v[180:183], v[124:127]
	v_mfma_f32_16x16x32_bf16 v[120:123], v[148:151], v[188:191], v[120:123]
	v_mfma_f32_16x16x32_bf16 v[116:119], v[156:159], v[188:191], v[116:119]
	v_mfma_f32_16x16x32_bf16 v[104:107], v[148:151], v[196:199], v[104:107]
	v_mfma_f32_16x16x32_bf16 v[100:103], v[156:159], v[196:199], v[100:103]
	v_mfma_f32_16x16x32_bf16 v[88:91], v[148:151], v[204:207], v[88:91]
	v_mfma_f32_16x16x32_bf16 v[84:87], v[156:159], v[204:207], v[84:87]
	v_mfma_f32_16x16x32_bf16 v[128:131], v[152:155], v[184:187], v[128:131]
	v_mfma_f32_16x16x32_bf16 v[124:127], v[176:179], v[184:187], v[124:127]
	v_mfma_f32_16x16x32_bf16 v[120:123], v[152:155], v[192:195], v[120:123]
	v_mfma_f32_16x16x32_bf16 v[116:119], v[176:179], v[192:195], v[116:119]
	v_mfma_f32_16x16x32_bf16 v[104:107], v[152:155], v[200:203], v[104:107]
	v_mfma_f32_16x16x32_bf16 v[100:103], v[176:179], v[200:203], v[100:103]
	s_setprio 3
	s_barrier
	v_mfma_f32_16x16x32_bf16 v[88:91], v[152:155], v[208:211], v[88:91]
	v_mfma_f32_16x16x32_bf16 v[84:87], v[176:179], v[208:211], v[84:87]
	s_setprio 2
	s_add_i32 s72, 0, 0x14000
	s_add_i32 s69, s69, s39
	ds_read_b128 v[212:215], v228 offset:16384
	ds_read_b128 v[216:219], v228 offset:17408
	ds_read_b128 v[220:223], v228 offset:18432
	ds_read_b128 v[224:227], v228 offset:19456
	s_mov_b32 m0, s69
	s_nop 0
	global_load_lds_dwordx4 v132, s[56:57]
	s_add_i32 m0, s69, 0x2000
	s_nop 0
	global_load_lds_dwordx4 v138, s[56:57]
	s_barrier
; #define PG8_STAGE(bufoff, gbase, voff) do { _Pragma("unroll") for (int _i = 0; _i < 2; ++_i) \
;         __builtin_amdgcn_global_load_lds((const unsigned*)((const char*)(gbase) + (voff)[_i]), (LAS unsigned*)(lds + (bufoff) + ldsw + _i * 8192), 16, 0, 0); } while (0)
; #define PG8_LDA(dst, b, h) do { _Pragma("unroll") for (int m = 0; m < 4; ++m) _Pragma("unroll") for (int k = 0; k < 2; ++k) dst[m][k] = *(const LAS bf16x8*)(lds + PG8_SA(b, h) + aoff + m * 2048 + k * 1024); } while (0)
; #define PG8_LDB(dst, b, h) do { _Pragma("unroll") for (int n = 0; n < 2; ++n) _Pragma("unroll") for (int k = 0; k < 2; ++k) dst[n][k] = *(const LAS bf16x8*)(lds + PG8_SB(b, h) + boff + n * 2048 + k * 1024); } while (0)
; #define PG8_MMA(ai, bj, At, Bt) do { __builtin_amdgcn_s_setprio(1); _Pragma("unroll") for (int m = 0; m < 4; ++m) _Pragma("unroll") for (int n = 0; n < 2; ++n) _Pragma("unroll") for (int k = 0; k < 2; ++k) \
;         acc[ai][bj][m][n] = __builtin_amdgcn_mfma_f32_16x16x32_bf16(Bt[n][k], At[m][k], acc[ai][bj][m][n], 0, 0, 0); __builtin_amdgcn_s_setprio(0); } while (0)
; #define PG8_WAIT_V(n) asm volatile("s_waitcnt vmcnt(" #n ")" ::: "memory")
; #define PG8_WAIT_L(n) asm volatile("s_waitcnt lgkmcnt(" #n ")" ::: "memory")
; #define PG8_BAR __builtin_amdgcn_s_barrier()
; #define PG8_SCHED __builtin_amdgcn_sched_barrier(0)
; template <class Epi, class Sched, int LD>
; __device__ __forceinline__ void gemm_phase(LAS unsigned char* lds, const Gemm g, const Sched& S, const Epi& E) {
;     ...
;             PG8_BAR; PG8_WAIT_L(0); PG8_MMA(0, 1, At, B1); PG8_BAR;
;             PG8_LDA(At, 0, 1); PG8_STAGE(PG8_SA(0, 0), a2, voffA);
;             PG8_BAR; PG8_WAIT_L(0); PG8_MMA(1, 0, At, B0); PG8_BAR; PG8_SCHED;
;             PG8_STAGE(PG8_SB(0, 1), b2 + hstep, voffB);
;             PG8_WAIT_V(6); PG8_BAR; PG8_MMA(1, 1, At, B1); PG8_BAR;
;             PG8_LDB(B0, 1, 0); PG8_SCHED; PG8_LDA(At, 1, 0); PG8_STAGE(PG8_SA(0, 1), a2 + hstep, voffA);
;             PG8_WAIT_L(8); PG8_BAR; PG8_WAIT_L(0); PG8_MMA(0, 0, At, B0); PG8_BAR; PG8_SCHED;
;             PG8_LDB(B1, 1, 1); PG8_STAGE(PG8_SB(1, 0), b3, voffB);
;             PG8_BAR; PG8_WAIT_L(0); PG8_MMA(0, 1, At, B1); PG8_BAR;
;             PG8_LDA(At, 1, 1); PG8_STAGE(PG8_SA(1, 0), a3, voffA);
;             PG8_BAR; PG8_WAIT_L(0); PG8_MMA(1, 0, At, B0); PG8_BAR; PG8_SCHED;
	s_waitcnt lgkmcnt(0)
	s_setprio 0
	v_mfma_f32_16x16x32_bf16 v[112:115], v[212:215], v[180:183], v[112:115]
	v_mfma_f32_16x16x32_bf16 v[108:111], v[220:223], v[180:183], v[108:111]
	v_mfma_f32_16x16x32_bf16 v[96:99], v[212:215], v[188:191], v[96:99]
	v_mfma_f32_16x16x32_bf16 v[92:95], v[220:223], v[188:191], v[92:95]
	v_mfma_f32_16x16x32_bf16 v[80:83], v[212:215], v[196:199], v[80:83]
	v_mfma_f32_16x16x32_bf16 v[76:79], v[220:223], v[196:199], v[76:79]
	v_mfma_f32_16x16x32_bf16 v[72:75], v[212:215], v[204:207], v[72:75]
	v_mfma_f32_16x16x32_bf16 v[68:71], v[220:223], v[204:207], v[68:71]
	v_mfma_f32_16x16x32_bf16 v[112:115], v[216:219], v[184:187], v[112:115]
	v_mfma_f32_16x16x32_bf16 v[108:111], v[224:227], v[184:187], v[108:111]
	v_mfma_f32_16x16x32_bf16 v[96:99], v[216:219], v[192:195], v[96:99]
	v_mfma_f32_16x16x32_bf16 v[92:95], v[224:227], v[192:195], v[92:95]
	v_mfma_f32_16x16x32_bf16 v[80:83], v[216:219], v[200:203], v[80:83]
	v_mfma_f32_16x16x32_bf16 v[76:79], v[224:227], v[200:203], v[76:79]
	v_mfma_f32_16x16x32_bf16 v[72:75], v[216:219], v[208:211], v[72:75]
	v_mfma_f32_16x16x32_bf16 v[68:71], v[224:227], v[208:211], v[68:71]
	s_setprio 2
	s_mov_b32 m0, s52
	s_barrier
	ds_read_b128 v[180:183], v146 offset:16384
	ds_read_b128 v[184:187], v146 offset:17408
	ds_read_b128 v[188:191], v146 offset:18432
	ds_read_b128 v[192:195], v146 offset:19456
	ds_read_b128 v[196:199], v146 offset:20480
	ds_read_b128 v[200:203], v146 offset:21504
	ds_read_b128 v[204:207], v146 offset:22528
	ds_read_b128 v[208:211], v146 offset:23552
	global_load_lds_dwordx4 v132, s[4:5]
	s_mov_b32 m0, s53
	s_nop 0
	global_load_lds_dwordx4 v138, s[4:5]
	s_waitcnt vmcnt(10)
	s_barrier
	s_waitcnt lgkmcnt(0)
	s_setprio 0
	v_mfma_f32_16x16x32_bf16 v[64:67], v[148:151], v[180:183], v[64:67]
	v_mfma_f32_16x16x32_bf16 v[60:63], v[156:159], v[180:183], v[60:63]
	v_mfma_f32_16x16x32_bf16 v[56:59], v[148:151], v[188:191], v[56:59]
	v_mfma_f32_16x16x32_bf16 v[52:55], v[156:159], v[188:191], v[52:55]
	v_mfma_f32_16x16x32_bf16 v[40:43], v[148:151], v[196:199], v[40:43]
	v_mfma_f32_16x16x32_bf16 v[36:39], v[156:159], v[196:199], v[36:39]
	v_mfma_f32_16x16x32_bf16 v[24:27], v[148:151], v[204:207], v[24:27]
	v_mfma_f32_16x16x32_bf16 v[20:23], v[156:159], v[204:207], v[20:23]
	v_mfma_f32_16x16x32_bf16 v[64:67], v[152:155], v[184:187], v[64:67]
	v_mfma_f32_16x16x32_bf16 v[60:63], v[176:179], v[184:187], v[60:63]
	v_mfma_f32_16x16x32_bf16 v[56:59], v[152:155], v[192:195], v[56:59]
	v_mfma_f32_16x16x32_bf16 v[52:55], v[176:179], v[192:195], v[52:55]
	v_mfma_f32_16x16x32_bf16 v[40:43], v[152:155], v[200:203], v[40:43]
	v_mfma_f32_16x16x32_bf16 v[36:39], v[176:179], v[200:203], v[36:39]
	s_setprio 3
	s_barrier
	v_mfma_f32_16x16x32_bf16 v[24:27], v[152:155], v[208:211], v[24:27]
	v_mfma_f32_16x16x32_bf16 v[20:23], v[176:179], v[208:211], v[20:23]
	s_setprio 2
	ds_read_b128 v[148:151], v228 offset:32768
	ds_read_b128 v[152:155], v228 offset:33792
	ds_read_b128 v[156:159], v228 offset:34816
	ds_read_b128 v[176:179], v228 offset:35840
	s_add_u32 s70, s56, 0x4000
	s_addc_u32 s71, s57, 0
	s_add_i32 s69, s72, s39
	s_mov_b32 m0, s69
	s_nop 0
	global_load_lds_dwordx4 v132, s[70:71]
	s_add_i32 m0, s69, 0x2000
	s_nop 0
	global_load_lds_dwordx4 v138, s[70:71]
	s_waitcnt vmcnt(6)
	s_barrier
	s_setprio 0
	v_mfma_f32_16x16x32_bf16 v[48:51], v[212:215], v[180:183], v[48:51]
	v_mfma_f32_16x16x32_bf16 v[44:47], v[220:223], v[180:183], v[44:47]
	v_mfma_f32_16x16x32_bf16 v[32:35], v[212:215], v[188:191], v[32:35]
	v_mfma_f32_16x16x32_bf16 v[28:31], v[220:223], v[188:191], v[28:31]
	v_mfma_f32_16x16x32_bf16 v[16:19], v[212:215], v[196:199], v[16:19]
	v_mfma_f32_16x16x32_bf16 v[12:15], v[220:223], v[196:199], v[12:15]
	v_mfma_f32_16x16x32_bf16 v[8:11], v[212:215], v[204:207], v[8:11]
	v_mfma_f32_16x16x32_bf16 v[4:7], v[220:223], v[204:207], v[4:7]
	v_mfma_f32_16x16x32_bf16 v[48:51], v[216:219], v[184:187], v[48:51]
	v_mfma_f32_16x16x32_bf16 v[44:47], v[224:227], v[184:187], v[44:47]
	v_mfma_f32_16x16x32_bf16 v[32:35], v[216:219], v[192:195], v[32:35]
	v_mfma_f32_16x16x32_bf16 v[28:31], v[224:227], v[192:195], v[28:31]
	v_mfma_f32_16x16x32_bf16 v[16:19], v[216:219], v[200:203], v[16:19]
	v_mfma_f32_16x16x32_bf16 v[12:15], v[224:227], v[200:203], v[12:15]
	v_mfma_f32_16x16x32_bf16 v[8:11], v[216:219], v[208:211], v[8:11]
	v_mfma_f32_16x16x32_bf16 v[4:7], v[224:227], v[208:211], v[4:7]
	s_setprio 2
	s_add_i32 s69, 0, 0x18000
	s_barrier
	s_add_u32 s4, s4, 0x4000
	s_addc_u32 s5, s5, 0
	s_mov_b32 m0, s60
	ds_read_b128 v[180:183], v146 offset:32768
	ds_read_b128 v[184:187], v146 offset:33792
	ds_read_b128 v[188:191], v146 offset:34816
	ds_read_b128 v[192:195], v146 offset:35840
	ds_read_b128 v[196:199], v146 offset:36864
	ds_read_b128 v[200:203], v146 offset:37888
	ds_read_b128 v[204:207], v146 offset:38912
	ds_read_b128 v[208:211], v146 offset:39936
	global_load_lds_dwordx4 v132, s[4:5]
	s_mov_b32 m0, s61
	s_nop 0
	global_load_lds_dwordx4 v138, s[4:5]
	s_waitcnt lgkmcnt(8)
	s_barrier
	s_waitcnt lgkmcnt(0)
	s_setprio 0
	v_mfma_f32_16x16x32_bf16 v[128:131], v[148:151], v[180:183], v[128:131]
	v_mfma_f32_16x16x32_bf16 v[124:127], v[156:159], v[180:183], v[124:127]
	v_mfma_f32_16x16x32_bf16 v[120:123], v[148:151], v[188:191], v[120:123]
	v_mfma_f32_16x16x32_bf16 v[116:119], v[156:159], v[188:191], v[116:119]
	v_mfma_f32_16x16x32_bf16 v[104:107], v[148:151], v[196:199], v[104:107]
	v_mfma_f32_16x16x32_bf16 v[100:103], v[156:159], v[196:199], v[100:103]
	v_mfma_f32_16x16x32_bf16 v[88:91], v[148:151], v[204:207], v[88:91]
	v_mfma_f32_16x16x32_bf16 v[84:87], v[156:159], v[204:207], v[84:87]
	v_mfma_f32_16x16x32_bf16 v[128:131], v[152:155], v[184:187], v[128:131]
	v_mfma_f32_16x16x32_bf16 v[124:127], v[176:179], v[184:187], v[124:127]
	v_mfma_f32_16x16x32_bf16 v[120:123], v[152:155], v[192:195], v[120:123]
	v_mfma_f32_16x16x32_bf16 v[116:119], v[176:179], v[192:195], v[116:119]
	v_mfma_f32_16x16x32_bf16 v[104:107], v[152:155], v[200:203], v[104:107]
	v_mfma_f32_16x16x32_bf16 v[100:103], v[176:179], v[200:203], v[100:103]
	s_setprio 3
	s_barrier
; #define PG8_STAGE(bufoff, gbase, voff) do { _Pragma("unroll") for (int _i = 0; _i < 2; ++_i) \
;         __builtin_amdgcn_global_load_lds((const unsigned*)((const char*)(gbase) + (voff)[_i]), (LAS unsigned*)(lds + (bufoff) + ldsw + _i * 8192), 16, 0, 0); } while (0)
; #define PG8_LDA(dst, b, h) do { _Pragma("unroll") for (int m = 0; m < 4; ++m) _Pragma("unroll") for (int k = 0; k < 2; ++k) dst[m][k] = *(const LAS bf16x8*)(lds + PG8_SA(b, h) + aoff + m * 2048 + k * 1024); } while (0)
; #define PG8_LDB(dst, b, h) do { _Pragma("unroll") for (int n = 0; n < 2; ++n) _Pragma("unroll") for (int k = 0; k < 2; ++k) dst[n][k] = *(const LAS bf16x8*)(lds + PG8_SB(b, h) + boff + n * 2048 + k * 1024); } while (0)
; #define PG8_MMA(ai, bj, At, Bt) do { __builtin_amdgcn_s_setprio(1); _Pragma("unroll") for (int m = 0; m < 4; ++m) _Pragma("unroll") for (int n = 0; n < 2; ++n) _Pragma("unroll") for (int k = 0; k < 2; ++k) \
;         acc[ai][bj][m][n] = __builtin_amdgcn_mfma_f32_16x16x32_bf16(Bt[n][k], At[m][k], acc[ai][bj][m][n], 0, 0, 0); __builtin_amdgcn_s_setprio(0); } while (0)
; #define PG8_WAIT_V(n) asm volatile("s_waitcnt vmcnt(" #n ")" ::: "memory")
; #define PG8_WAIT_L(n) asm volatile("s_waitcnt lgkmcnt(" #n ")" ::: "memory")
; #define PG8_BAR __builtin_amdgcn_s_barrier()
; #define PG8_SCHED __builtin_amdgcn_sched_barrier(0)
; template <class Epi, class Sched, int LD>
; __device__ __forceinline__ void gemm_phase(LAS unsigned char* lds, const Gemm g, const Sched& S, const Epi& E) {
;     ...
;             PG8_WAIT_L(8); PG8_BAR; PG8_WAIT_L(0); PG8_MMA(0, 0, At, B0); PG8_BAR; PG8_SCHED;
;             PG8_LDB(B1, 1, 1); PG8_STAGE(PG8_SB(1, 0), b3, voffB);
;             PG8_BAR; PG8_WAIT_L(0); PG8_MMA(0, 1, At, B1); PG8_BAR;
;             PG8_LDA(At, 1, 1); PG8_STAGE(PG8_SA(1, 0), a3, voffA);
;             PG8_BAR; PG8_WAIT_L(0); PG8_MMA(1, 0, At, B0); PG8_BAR; PG8_SCHED;
;             PG8_STAGE(PG8_SB(1, 1), b3 + hstep, voffB);
;             PG8_WAIT_V(6); PG8_BAR; PG8_MMA(1, 1, At, B1); PG8_BAR;
	v_mfma_f32_16x16x32_bf16 v[88:91], v[152:155], v[208:211], v[88:91]
	v_mfma_f32_16x16x32_bf16 v[84:87], v[176:179], v[208:211], v[84:87]
	s_setprio 2
	s_add_i32 s70, 0, 0x1c000
	s_add_u32 s4, s56, 0x8000
	s_addc_u32 s5, s57, 0
	s_add_i32 s69, s69, s39
	ds_read_b128 v[212:215], v228 offset:49152
	ds_read_b128 v[216:219], v228 offset:50176
	ds_read_b128 v[220:223], v228 offset:51200
	ds_read_b128 v[224:227], v228 offset:52224
	s_mov_b32 m0, s69
	s_nop 0
	global_load_lds_dwordx4 v132, s[4:5]
	s_add_i32 m0, s69, 0x2000
	s_nop 0
	global_load_lds_dwordx4 v138, s[4:5]
	s_barrier
	s_waitcnt lgkmcnt(0)
	s_setprio 0
	v_mfma_f32_16x16x32_bf16 v[112:115], v[212:215], v[180:183], v[112:115]
	v_mfma_f32_16x16x32_bf16 v[108:111], v[220:223], v[180:183], v[108:111]
	v_mfma_f32_16x16x32_bf16 v[96:99], v[212:215], v[188:191], v[96:99]
	v_mfma_f32_16x16x32_bf16 v[92:95], v[220:223], v[188:191], v[92:95]
	v_mfma_f32_16x16x32_bf16 v[80:83], v[212:215], v[196:199], v[80:83]
	v_mfma_f32_16x16x32_bf16 v[76:79], v[220:223], v[196:199], v[76:79]
	v_mfma_f32_16x16x32_bf16 v[72:75], v[212:215], v[204:207], v[72:75]
	v_mfma_f32_16x16x32_bf16 v[68:71], v[220:223], v[204:207], v[68:71]
	v_mfma_f32_16x16x32_bf16 v[112:115], v[216:219], v[184:187], v[112:115]
	v_mfma_f32_16x16x32_bf16 v[108:111], v[224:227], v[184:187], v[108:111]
	v_mfma_f32_16x16x32_bf16 v[96:99], v[216:219], v[192:195], v[96:99]
	v_mfma_f32_16x16x32_bf16 v[92:95], v[224:227], v[192:195], v[92:95]
	v_mfma_f32_16x16x32_bf16 v[80:83], v[216:219], v[200:203], v[80:83]
	v_mfma_f32_16x16x32_bf16 v[76:79], v[224:227], v[200:203], v[76:79]
	v_mfma_f32_16x16x32_bf16 v[72:75], v[216:219], v[208:211], v[72:75]
	v_mfma_f32_16x16x32_bf16 v[68:71], v[224:227], v[208:211], v[68:71]
	s_setprio 2
	s_mov_b32 m0, s64
	s_barrier
	ds_read_b128 v[180:183], v146 offset:49152
	ds_read_b128 v[184:187], v146 offset:50176
	ds_read_b128 v[188:191], v146 offset:51200
	ds_read_b128 v[192:195], v146 offset:52224
	ds_read_b128 v[196:199], v146 offset:53248
	ds_read_b128 v[200:203], v146 offset:54272
	ds_read_b128 v[204:207], v146 offset:55296
	ds_read_b128 v[208:211], v146 offset:56320
	global_load_lds_dwordx4 v132, s[58:59]
	s_mov_b32 m0, s65
	s_nop 0
	global_load_lds_dwordx4 v138, s[58:59]
	s_waitcnt vmcnt(10)
	s_barrier
	s_waitcnt lgkmcnt(0)
	s_setprio 0
	v_mfma_f32_16x16x32_bf16 v[64:67], v[148:151], v[180:183], v[64:67]
	v_mfma_f32_16x16x32_bf16 v[60:63], v[156:159], v[180:183], v[60:63]
	v_mfma_f32_16x16x32_bf16 v[56:59], v[148:151], v[188:191], v[56:59]
	v_mfma_f32_16x16x32_bf16 v[52:55], v[156:159], v[188:191], v[52:55]
	v_mfma_f32_16x16x32_bf16 v[40:43], v[148:151], v[196:199], v[40:43]
	v_mfma_f32_16x16x32_bf16 v[36:39], v[156:159], v[196:199], v[36:39]
	v_mfma_f32_16x16x32_bf16 v[24:27], v[148:151], v[204:207], v[24:27]
	v_mfma_f32_16x16x32_bf16 v[20:23], v[156:159], v[204:207], v[20:23]
	v_mfma_f32_16x16x32_bf16 v[64:67], v[152:155], v[184:187], v[64:67]
	v_mfma_f32_16x16x32_bf16 v[60:63], v[176:179], v[184:187], v[60:63]
	v_mfma_f32_16x16x32_bf16 v[56:59], v[152:155], v[192:195], v[56:59]
	v_mfma_f32_16x16x32_bf16 v[52:55], v[176:179], v[192:195], v[52:55]
	v_mfma_f32_16x16x32_bf16 v[40:43], v[152:155], v[200:203], v[40:43]
	v_mfma_f32_16x16x32_bf16 v[36:39], v[176:179], v[200:203], v[36:39]
	s_setprio 3
	s_barrier
	v_mfma_f32_16x16x32_bf16 v[24:27], v[152:155], v[208:211], v[24:27]
	v_mfma_f32_16x16x32_bf16 v[20:23], v[176:179], v[208:211], v[20:23]
	s_setprio 2
	ds_read_b128 v[148:151], v228
	ds_read_b128 v[152:155], v228 offset:1024
	ds_read_b128 v[156:159], v228 offset:2048
	ds_read_b128 v[176:179], v228 offset:3072
	s_add_u32 s4, s56, 0xc000
	s_addc_u32 s5, s57, 0
	s_add_i32 s56, s70, s39
	s_mov_b32 m0, s56
	s_nop 0
	global_load_lds_dwordx4 v132, s[4:5]
	s_add_i32 m0, s56, 0x2000
	s_nop 0
	global_load_lds_dwordx4 v138, s[4:5]
	s_waitcnt vmcnt(6)
	s_barrier
; #define PG8_STAGE(bufoff, gbase, voff) do { _Pragma("unroll") for (int _i = 0; _i < 2; ++_i) \
;         __builtin_amdgcn_global_load_lds((const unsigned*)((const char*)(gbase) + (voff)[_i]), (LAS unsigned*)(lds + (bufoff) + ldsw + _i * 8192), 16, 0, 0); } while (0)
; #define PG8_MMA(ai, bj, At, Bt) do { __builtin_amdgcn_s_setprio(1); _Pragma("unroll") for (int m = 0; m < 4; ++m) _Pragma("unroll") for (int n = 0; n < 2; ++n) _Pragma("unroll") for (int k = 0; k < 2; ++k) \
;         acc[ai][bj][m][n] = __builtin_amdgcn_mfma_f32_16x16x32_bf16(Bt[n][k], At[m][k], acc[ai][bj][m][n], 0, 0, 0); __builtin_amdgcn_s_setprio(0); } while (0)
; #define PG8_WAIT_V(n) asm volatile("s_waitcnt vmcnt(" #n ")" ::: "memory")
; #define PG8_BAR __builtin_amdgcn_s_barrier()
;     __device__ __forceinline__ void operator()(const f32x4 (&acc)[2][2][4][2], const Unit& u, int wr, int wc, int fr, int fq) const {
;     ...
;         } else if (wc == 0) {
; #pragma unroll
;             for (int ai = 0; ai < 2; ++ai)
; #pragma unroll
;                 for (int m = 0; m < 4; ++m) {
;                     float* rowp = DT + (size_t)(row0 + ai * HALF + m * 16) * 32 + 8 * fq;
;                     *(f32x4*)rowp = acc[ai][0][m][0]; *(f32x4*)(rowp + 4) = acc[ai][0][m][1];
;                 }
;         }
; template <class Epi, class Sched, int LD>
; __device__ __forceinline__ void gemm_phase(LAS unsigned char* lds, const Gemm g, const Sched& S, const Epi& E) {
;     ...
;             PG8_STAGE(PG8_SB(1, 1), b3 + hstep, voffB);
;             PG8_WAIT_V(6); PG8_BAR; PG8_MMA(1, 1, At, B1); PG8_BAR;
;         }
;         E(acc, cur, wr, wc, fr, fq);
	s_setprio 0
	v_mfma_f32_16x16x32_bf16 v[48:51], v[212:215], v[180:183], v[48:51]
	v_mfma_f32_16x16x32_bf16 v[44:47], v[220:223], v[180:183], v[44:47]
	v_mfma_f32_16x16x32_bf16 v[32:35], v[212:215], v[188:191], v[32:35]
	v_mfma_f32_16x16x32_bf16 v[28:31], v[220:223], v[188:191], v[28:31]
	v_mfma_f32_16x16x32_bf16 v[16:19], v[212:215], v[196:199], v[16:19]
	v_mfma_f32_16x16x32_bf16 v[12:15], v[220:223], v[196:199], v[12:15]
	v_mfma_f32_16x16x32_bf16 v[8:11], v[212:215], v[204:207], v[8:11]
	v_mfma_f32_16x16x32_bf16 v[4:7], v[220:223], v[204:207], v[4:7]
	v_mfma_f32_16x16x32_bf16 v[48:51], v[216:219], v[184:187], v[48:51]
	v_mfma_f32_16x16x32_bf16 v[44:47], v[224:227], v[184:187], v[44:47]
	v_mfma_f32_16x16x32_bf16 v[32:35], v[216:219], v[192:195], v[32:35]
	v_mfma_f32_16x16x32_bf16 v[28:31], v[224:227], v[192:195], v[28:31]
	v_mfma_f32_16x16x32_bf16 v[16:19], v[216:219], v[200:203], v[16:19]
	v_mfma_f32_16x16x32_bf16 v[12:15], v[224:227], v[200:203], v[12:15]
	v_mfma_f32_16x16x32_bf16 v[8:11], v[216:219], v[208:211], v[8:11]
	v_mfma_f32_16x16x32_bf16 v[4:7], v[224:227], v[208:211], v[4:7]
	s_setprio 2
	s_add_i32 s49, s49, 2
	s_add_u32 s54, s54, 0x10000
	s_addc_u32 s55, s55, 0
	s_add_u32 s29, s29, 0x10000
	s_addc_u32 s47, s47, 0
	s_cmp_gt_u32 s49, 29
	s_barrier
	s_cbranch_scc0 .LBB0_501
	s_setprio 0
	v_lshl_add_u32 v142, s68, 8, v137
	s_cmp_gt_i32 s67, 35
	s_mov_b64 s[4:5], -1
	s_cbranch_scc0 .LBB0_506
	s_andn2_b64 vcc, exec, s[42:43]
	s_cbranch_vccnz .LBB0_505
	v_or_b32_e32 v150, 16, v142
	v_ashrrev_i32_e32 v143, 31, v142
	v_ashrrev_i32_e32 v151, 31, v150
	v_lshlrev_b64 v[148:149], 7, v[142:143]
	v_lshlrev_b64 v[150:151], 7, v[150:151]
	v_lshl_add_u64 v[148:149], v[140:141], 0, v[148:149]
	v_lshl_add_u64 v[150:151], v[140:141], 0, v[150:151]
	global_store_dwordx4 v[148:149], v[128:131], off
	global_store_dwordx4 v[148:149], v[124:127], off offset:16
	global_store_dwordx4 v[150:151], v[120:123], off
	global_store_dwordx4 v[150:151], v[116:119], off offset:16
	v_or_b32_e32 v150, 32, v142
	v_ashrrev_i32_e32 v151, 31, v150
	v_lshlrev_b64 v[150:151], 7, v[150:151]
	v_lshl_add_u64 v[150:151], v[140:141], 0, v[150:151]
	global_store_dwordx4 v[150:151], v[104:107], off
	global_store_dwordx4 v[150:151], v[100:103], off offset:16
	v_or_b32_e32 v150, 48, v142
	v_ashrrev_i32_e32 v151, 31, v150
	v_lshlrev_b64 v[150:151], 7, v[150:151]
	v_lshl_add_u64 v[150:151], v[140:141], 0, v[150:151]
	s_mov_b64 s[4:5], 0x4000
	global_store_dwordx4 v[150:151], v[88:91], off
	global_store_dwordx4 v[150:151], v[84:87], off offset:16
	v_lshl_add_u64 v[150:151], v[148:149], 0, s[4:5]
	s_movk_i32 s4, 0x4000
	v_add_co_u32_e32 v152, vcc, s4, v148
	s_mov_b64 s[4:5], 0x4800
	s_nop 0
	v_addc_co_u32_e32 v153, vcc, 0, v149, vcc
	global_store_dwordx4 v[152:153], v[64:67], off
	global_store_dwordx4 v[150:151], v[60:63], off offset:16
	v_lshl_add_u64 v[150:151], v[148:149], 0, s[4:5]
	global_store_dwordx4 v[152:153], v[56:59], off offset:2048
	global_store_dwordx4 v[150:151], v[52:55], off offset:16
	s_mov_b64 s[4:5], 0x5000
	v_add_co_u32_e32 v152, vcc, 0x5000, v148
	v_lshl_add_u64 v[150:151], v[148:149], 0, s[4:5]
	s_nop 0
	v_addc_co_u32_e32 v153, vcc, 0, v149, vcc
	s_mov_b64 s[4:5], 0x5800
	global_store_dwordx4 v[152:153], v[40:43], off
	global_store_dwordx4 v[150:151], v[36:39], off offset:16
	v_lshl_add_u64 v[148:149], v[148:149], 0, s[4:5]
	global_store_dwordx4 v[152:153], v[24:27], off offset:2048
	global_store_dwordx4 v[148:149], v[20:23], off offset:16

; #define PG8_STAGE(bufoff, gbase, voff) do { _Pragma("unroll") for (int _i = 0; _i < 2; ++_i) \
;         __builtin_amdgcn_global_load_lds((const unsigned*)((const char*)(gbase) + (voff)[_i]), (LAS unsigned*)(lds + (bufoff) + ldsw + _i * 8192), 16, 0, 0); } while (0)
; #define PG8_LDA(dst, b, h) do { _Pragma("unroll") for (int m = 0; m < 4; ++m) _Pragma("unroll") for (int k = 0; k < 2; ++k) dst[m][k] = *(const LAS bf16x8*)(lds + PG8_SA(b, h) + aoff + m * 2048 + k * 1024); } while (0)
; #define PG8_LDB(dst, b, h) do { _Pragma("unroll") for (int n = 0; n < 2; ++n) _Pragma("unroll") for (int k = 0; k < 2; ++k) dst[n][k] = *(const LAS bf16x8*)(lds + PG8_SB(b, h) + boff + n * 2048 + k * 1024); } while (0)
; #define PG8_SCHED __builtin_amdgcn_sched_barrier(0)
; template <class Epi, class Sched, int LD>
; __device__ __forceinline__ void gemm_phase(LAS unsigned char* lds, const Gemm g, const Sched& S, const Epi& E) {
;     ...
;             PG8_LDB(B0, 0, 0); PG8_SCHED; PG8_LDA(At, 0, 0); PG8_STAGE(PG8_SA(1, 1), a1 + hstep, voffA);
;     ...
; #pragma unroll
;         for (int a = 0; a < 2; ++a)
; #pragma unroll
;             for (int b = 0; b < 2; ++b)
; #pragma unroll
;                 for (int m = 0; m < 4; ++m)
; #pragma unroll
;                     for (int n = 0; n < 2; ++n) acc[a][b][m][n] = (f32x4){0.f, 0.f, 0.f, 0.f};
;         cur = nxt; cA = nA; cB = nB; ++ui;
.LBB0_774:
	s_add_i32 s68, s65, -2
	s_add_u32 s46, s46, 0xc000
	s_addc_u32 s47, s47, 0
	s_add_u32 s69, s48, 0x10000
	v_mov_b32_e32 v4, 0
	s_addc_u32 s70, s49, 0
	s_mov_b32 s4, 0
	v_mov_b32_e32 v5, v4
	v_mov_b32_e32 v6, v4
	v_mov_b32_e32 v7, v4
	v_mov_b32_e32 v8, v4
	v_mov_b32_e32 v9, v4
	v_mov_b32_e32 v10, v4
	v_mov_b32_e32 v11, v4
	v_mov_b32_e32 v20, v4
	v_mov_b32_e32 v21, v4
	v_mov_b32_e32 v22, v4
	v_mov_b32_e32 v23, v4
	v_mov_b32_e32 v24, v4
	v_mov_b32_e32 v25, v4
	v_mov_b32_e32 v26, v4
	v_mov_b32_e32 v27, v4
	v_mov_b32_e32 v36, v4
	v_mov_b32_e32 v37, v4
	v_mov_b32_e32 v38, v4
	v_mov_b32_e32 v39, v4
	v_mov_b32_e32 v40, v4
	v_mov_b32_e32 v41, v4
	v_mov_b32_e32 v42, v4
	v_mov_b32_e32 v43, v4
	v_mov_b32_e32 v52, v4
	v_mov_b32_e32 v53, v4
	v_mov_b32_e32 v54, v4
	v_mov_b32_e32 v55, v4
	v_mov_b32_e32 v56, v4
	v_mov_b32_e32 v57, v4
	v_mov_b32_e32 v58, v4
	v_mov_b32_e32 v59, v4
	v_mov_b32_e32 v12, v4
	v_mov_b32_e32 v13, v4
	v_mov_b32_e32 v14, v4
	v_mov_b32_e32 v15, v4
	v_mov_b32_e32 v16, v4
	v_mov_b32_e32 v17, v4
	v_mov_b32_e32 v18, v4
	v_mov_b32_e32 v19, v4
	v_mov_b32_e32 v28, v4
	v_mov_b32_e32 v29, v4
	v_mov_b32_e32 v30, v4
	v_mov_b32_e32 v31, v4
	v_mov_b32_e32 v32, v4
	v_mov_b32_e32 v33, v4
	v_mov_b32_e32 v34, v4
	v_mov_b32_e32 v35, v4
	v_mov_b32_e32 v44, v4
	v_mov_b32_e32 v45, v4
	v_mov_b32_e32 v46, v4
	v_mov_b32_e32 v47, v4
	v_mov_b32_e32 v48, v4
	v_mov_b32_e32 v49, v4
	v_mov_b32_e32 v50, v4
	v_mov_b32_e32 v51, v4
	v_mov_b32_e32 v60, v4
	v_mov_b32_e32 v61, v4
	v_mov_b32_e32 v62, v4
	v_mov_b32_e32 v63, v4
	v_mov_b32_e32 v64, v4
	v_mov_b32_e32 v65, v4
	v_mov_b32_e32 v66, v4
	v_mov_b32_e32 v67, v4
	v_mov_b32_e32 v68, v4
	v_mov_b32_e32 v69, v4
	v_mov_b32_e32 v70, v4
	v_mov_b32_e32 v71, v4
	v_mov_b32_e32 v72, v4
	v_mov_b32_e32 v73, v4
	v_mov_b32_e32 v74, v4
	v_mov_b32_e32 v75, v4
	v_mov_b32_e32 v84, v4
	v_mov_b32_e32 v85, v4
	v_mov_b32_e32 v86, v4
	v_mov_b32_e32 v87, v4
	v_mov_b32_e32 v88, v4
	v_mov_b32_e32 v89, v4
	v_mov_b32_e32 v90, v4
	v_mov_b32_e32 v91, v4
	v_mov_b32_e32 v100, v4
	v_mov_b32_e32 v101, v4
	v_mov_b32_e32 v102, v4
	v_mov_b32_e32 v103, v4
	v_mov_b32_e32 v104, v4
	v_mov_b32_e32 v105, v4
	v_mov_b32_e32 v106, v4
	v_mov_b32_e32 v107, v4
	v_mov_b32_e32 v116, v4
	v_mov_b32_e32 v117, v4
	v_mov_b32_e32 v118, v4
	v_mov_b32_e32 v119, v4
	v_mov_b32_e32 v120, v4
	v_mov_b32_e32 v121, v4
	v_mov_b32_e32 v122, v4
	v_mov_b32_e32 v123, v4
	v_mov_b32_e32 v76, v4
	v_mov_b32_e32 v77, v4
	v_mov_b32_e32 v78, v4
	v_mov_b32_e32 v79, v4
	v_mov_b32_e32 v80, v4
	v_mov_b32_e32 v81, v4
	v_mov_b32_e32 v82, v4
	v_mov_b32_e32 v83, v4
	v_mov_b32_e32 v92, v4
	v_mov_b32_e32 v93, v4
	v_mov_b32_e32 v94, v4
	v_mov_b32_e32 v95, v4
	v_mov_b32_e32 v96, v4
	v_mov_b32_e32 v97, v4
	v_mov_b32_e32 v98, v4
	v_mov_b32_e32 v99, v4
	v_mov_b32_e32 v108, v4
	v_mov_b32_e32 v109, v4
	v_mov_b32_e32 v110, v4
	v_mov_b32_e32 v111, v4
	v_mov_b32_e32 v112, v4
	v_mov_b32_e32 v113, v4
	v_mov_b32_e32 v114, v4
	v_mov_b32_e32 v115, v4
	v_mov_b32_e32 v124, v4
	v_mov_b32_e32 v125, v4
	v_mov_b32_e32 v126, v4
	v_mov_b32_e32 v127, v4
	v_mov_b32_e32 v128, v4
	v_mov_b32_e32 v129, v4
	v_mov_b32_e32 v130, v4
	v_mov_b32_e32 v131, v4
	ds_read_b128 v[140:143], v228
	ds_read_b128 v[150:153], v228 offset:1024
	ds_read_b128 v[154:157], v228 offset:2048
	ds_read_b128 v[176:179], v228 offset:3072

; #define PG8_STAGE(bufoff, gbase, voff) do { _Pragma("unroll") for (int _i = 0; _i < 2; ++_i) \
;         __builtin_amdgcn_global_load_lds((const unsigned*)((const char*)(gbase) + (voff)[_i]), (LAS unsigned*)(lds + (bufoff) + ldsw + _i * 8192), 16, 0, 0); } while (0)
; #define PG8_LDA(dst, b, h) do { _Pragma("unroll") for (int m = 0; m < 4; ++m) _Pragma("unroll") for (int k = 0; k < 2; ++k) dst[m][k] = *(const LAS bf16x8*)(lds + PG8_SA(b, h) + aoff + m * 2048 + k * 1024); } while (0)
; #define PG8_LDB(dst, b, h) do { _Pragma("unroll") for (int n = 0; n < 2; ++n) _Pragma("unroll") for (int k = 0; k < 2; ++k) dst[n][k] = *(const LAS bf16x8*)(lds + PG8_SB(b, h) + boff + n * 2048 + k * 1024); } while (0)
; #define PG8_WAIT_L(n) asm volatile("s_waitcnt lgkmcnt(" #n ")" ::: "memory")
; template <class Epi, class Sched, int LD>
; __device__ __forceinline__ void gemm_phase(LAS unsigned char* lds, const Gemm g, const Sched& S, const Epi& E) {
;     ...
;         const bool has_next = S.next(ui + 1, nxt);
;         const char* nA = has_next ? (const char*)g.A + (size_t)nxt.pm * tstep + (size_t)(nxt.kofs / BK) * kstep : cA; const char* nB = has_next ? (const char*)g.Bt + (size_t)nxt.pn * tstep + (size_t)(nxt.kofs / BK) * kstep : cB;
;         const int nt = cur.nt;
;         for (int t = 0; t < nt; t += 2) {
;             const bool last = (t == nt - 2);
;             const char* a1 = cA + (size_t)(t + 1) * kstep;
;             const char* a2 = last ? nA : cA + (size_t)(t + 2) * kstep; const char* b2 = last ? nB : cB + (size_t)(t + 2) * kstep;
;             const char* a3 = a2 + kstep; const char* b3 = b2 + kstep;
;             PG8_LDB(B0, 0, 0); PG8_SCHED; PG8_LDA(At, 0, 0); PG8_STAGE(PG8_SA(1, 1), a1 + hstep, voffA);
;             PG8_WAIT_L(8); PG8_BAR; PG8_WAIT_L(0); PG8_MMA(0, 0, At, B0); PG8_BAR; PG8_SCHED;
;             PG8_LDB(B1, 0, 1); PG8_STAGE(PG8_SB(0, 0), b2, voffB);
;             PG8_BAR; PG8_WAIT_L(0); PG8_MMA(0, 1, At, B1); PG8_BAR;
;             PG8_LDA(At, 0, 1); PG8_STAGE(PG8_SA(0, 0), a2, voffA);
;     ...
; #pragma unroll
;         for (int a = 0; a < 2; ++a)
; #pragma unroll
;             for (int b = 0; b < 2; ++b)
; #pragma unroll
;                 for (int m = 0; m < 4; ++m)
; #pragma unroll
;                     for (int n = 0; n < 2; ++n) acc[a][b][m][n] = (f32x4){0.f, 0.f, 0.f, 0.f};
;         cur = nxt; cA = nA; cB = nB; ++ui;
.LBB0_898:
	s_add_u32 s50, s4, 0xc000
	s_addc_u32 s51, s5, 0
	s_add_u32 s45, s54, 0x10000
	v_mov_b32_e32 v4, 0
	s_addc_u32 s47, s55, 0
	s_mov_b32 s70, -2
	v_mov_b32_e32 v5, v4
	v_mov_b32_e32 v6, v4
	v_mov_b32_e32 v7, v4
	v_mov_b32_e32 v12, v4
	v_mov_b32_e32 v13, v4
	v_mov_b32_e32 v14, v4
	v_mov_b32_e32 v15, v4
	v_mov_b32_e32 v20, v4
	v_mov_b32_e32 v21, v4
	v_mov_b32_e32 v22, v4
	v_mov_b32_e32 v23, v4
	v_mov_b32_e32 v28, v4
	v_mov_b32_e32 v29, v4
	v_mov_b32_e32 v30, v4
	v_mov_b32_e32 v31, v4
	v_mov_b32_e32 v36, v4
	v_mov_b32_e32 v37, v4
	v_mov_b32_e32 v38, v4
	v_mov_b32_e32 v39, v4
	v_mov_b32_e32 v44, v4
	v_mov_b32_e32 v45, v4
	v_mov_b32_e32 v46, v4
	v_mov_b32_e32 v47, v4
	v_mov_b32_e32 v52, v4
	v_mov_b32_e32 v53, v4
	v_mov_b32_e32 v54, v4
	v_mov_b32_e32 v55, v4
	v_mov_b32_e32 v60, v4
	v_mov_b32_e32 v61, v4
	v_mov_b32_e32 v62, v4
	v_mov_b32_e32 v63, v4
	v_mov_b32_e32 v8, v4
	v_mov_b32_e32 v9, v4
	v_mov_b32_e32 v10, v4
	v_mov_b32_e32 v11, v4
	v_mov_b32_e32 v16, v4
	v_mov_b32_e32 v17, v4
	v_mov_b32_e32 v18, v4
	v_mov_b32_e32 v19, v4
	v_mov_b32_e32 v24, v4
	v_mov_b32_e32 v25, v4
	v_mov_b32_e32 v26, v4
	v_mov_b32_e32 v27, v4
	v_mov_b32_e32 v32, v4
	v_mov_b32_e32 v33, v4
	v_mov_b32_e32 v34, v4
	v_mov_b32_e32 v35, v4
	v_mov_b32_e32 v40, v4
	v_mov_b32_e32 v41, v4
	v_mov_b32_e32 v42, v4
	v_mov_b32_e32 v43, v4
	v_mov_b32_e32 v48, v4
	v_mov_b32_e32 v49, v4
	v_mov_b32_e32 v50, v4
	v_mov_b32_e32 v51, v4
	v_mov_b32_e32 v56, v4
	v_mov_b32_e32 v57, v4
	v_mov_b32_e32 v58, v4
	v_mov_b32_e32 v59, v4
	v_mov_b32_e32 v64, v4
	v_mov_b32_e32 v65, v4
	v_mov_b32_e32 v66, v4
	v_mov_b32_e32 v67, v4
	v_mov_b32_e32 v68, v4
	v_mov_b32_e32 v69, v4
	v_mov_b32_e32 v70, v4
	v_mov_b32_e32 v71, v4
	v_mov_b32_e32 v76, v4
	v_mov_b32_e32 v77, v4
	v_mov_b32_e32 v78, v4
	v_mov_b32_e32 v79, v4
	v_mov_b32_e32 v84, v4
	v_mov_b32_e32 v85, v4
	v_mov_b32_e32 v86, v4
	v_mov_b32_e32 v87, v4
	v_mov_b32_e32 v92, v4
	v_mov_b32_e32 v93, v4
	v_mov_b32_e32 v94, v4
	v_mov_b32_e32 v95, v4
	v_mov_b32_e32 v100, v4
	v_mov_b32_e32 v101, v4
	v_mov_b32_e32 v102, v4
	v_mov_b32_e32 v103, v4
	v_mov_b32_e32 v108, v4
	v_mov_b32_e32 v109, v4
	v_mov_b32_e32 v110, v4
	v_mov_b32_e32 v111, v4
	v_mov_b32_e32 v116, v4
	v_mov_b32_e32 v117, v4
	v_mov_b32_e32 v118, v4
	v_mov_b32_e32 v119, v4
	v_mov_b32_e32 v124, v4
	v_mov_b32_e32 v125, v4
	v_mov_b32_e32 v126, v4
	v_mov_b32_e32 v127, v4
	v_mov_b32_e32 v72, v4
	v_mov_b32_e32 v73, v4
	v_mov_b32_e32 v74, v4
	v_mov_b32_e32 v75, v4
	v_mov_b32_e32 v80, v4
	v_mov_b32_e32 v81, v4
	v_mov_b32_e32 v82, v4
	v_mov_b32_e32 v83, v4
	v_mov_b32_e32 v88, v4
	v_mov_b32_e32 v89, v4
	v_mov_b32_e32 v90, v4
	v_mov_b32_e32 v91, v4
	v_mov_b32_e32 v96, v4
	v_mov_b32_e32 v97, v4
	v_mov_b32_e32 v98, v4
	v_mov_b32_e32 v99, v4
	v_mov_b32_e32 v104, v4
	v_mov_b32_e32 v105, v4
	v_mov_b32_e32 v106, v4
	v_mov_b32_e32 v107, v4
	v_mov_b32_e32 v112, v4
	v_mov_b32_e32 v113, v4
	v_mov_b32_e32 v114, v4
	v_mov_b32_e32 v115, v4
	v_mov_b32_e32 v120, v4
	v_mov_b32_e32 v121, v4
	v_mov_b32_e32 v122, v4
	v_mov_b32_e32 v123, v4
	v_mov_b32_e32 v128, v4
	v_mov_b32_e32 v129, v4
	v_mov_b32_e32 v130, v4
	v_mov_b32_e32 v131, v4
	ds_read_b128 v[146:149], v228
	ds_read_b128 v[150:153], v228 offset:1024
	ds_read_b128 v[154:157], v228 offset:2048
	ds_read_b128 v[176:179], v228 offset:3072
.LBB0_899:
	s_add_u32 s4, s50, 0x4000
	s_addc_u32 s5, s51, 0
	s_cmp_eq_u32 s70, 28
	s_cselect_b32 s4, s48, s4
	s_cselect_b32 s5, s49, s5
	s_cselect_b32 s54, s40, s45
	s_cselect_b32 s55, s41, s47
	s_add_u32 s56, s4, 0x8000
	s_addc_u32 s57, s5, 0
	s_add_i32 s71, 0, 0x10000
	s_add_i32 m0, s29, 0xc000
	ds_read_b128 v[180:183], v144
	ds_read_b128 v[184:187], v144 offset:1024
	ds_read_b128 v[188:191], v144 offset:2048
	ds_read_b128 v[192:195], v144 offset:3072
	ds_read_b128 v[196:199], v144 offset:4096
	ds_read_b128 v[200:203], v144 offset:5120
	ds_read_b128 v[204:207], v144 offset:6144
	ds_read_b128 v[208:211], v144 offset:7168
	global_load_lds_dwordx4 v138, s[50:51]
	s_add_i32 m0, s29, 0xe000
	s_nop 0
	global_load_lds_dwordx4 v140, s[50:51]
	s_waitcnt lgkmcnt(8)
	s_barrier
	s_waitcnt lgkmcnt(0)
	s_setprio 0
	v_mfma_f32_16x16x32_bf16 v[128:131], v[146:149], v[180:183], v[128:131]
	v_mfma_f32_16x16x32_bf16 v[120:123], v[154:157], v[180:183], v[120:123]
	v_mfma_f32_16x16x32_bf16 v[112:115], v[146:149], v[188:191], v[112:115]
	v_mfma_f32_16x16x32_bf16 v[104:107], v[154:157], v[188:191], v[104:107]
	v_mfma_f32_16x16x32_bf16 v[96:99], v[146:149], v[196:199], v[96:99]
	v_mfma_f32_16x16x32_bf16 v[88:91], v[154:157], v[196:199], v[88:91]
	v_mfma_f32_16x16x32_bf16 v[80:83], v[146:149], v[204:207], v[80:83]
	v_mfma_f32_16x16x32_bf16 v[72:75], v[154:157], v[204:207], v[72:75]
	v_mfma_f32_16x16x32_bf16 v[128:131], v[150:153], v[184:187], v[128:131]
	v_mfma_f32_16x16x32_bf16 v[120:123], v[176:179], v[184:187], v[120:123]
	v_mfma_f32_16x16x32_bf16 v[112:115], v[150:153], v[192:195], v[112:115]
	v_mfma_f32_16x16x32_bf16 v[104:107], v[176:179], v[192:195], v[104:107]
	v_mfma_f32_16x16x32_bf16 v[96:99], v[150:153], v[200:203], v[96:99]
	v_mfma_f32_16x16x32_bf16 v[88:91], v[176:179], v[200:203], v[88:91]
	s_setprio 3
	s_barrier
	v_mfma_f32_16x16x32_bf16 v[80:83], v[150:153], v[208:211], v[80:83]
	v_mfma_f32_16x16x32_bf16 v[72:75], v[176:179], v[208:211], v[72:75]
	s_setprio 2
	s_add_i32 s74, 0, 0x14000
	s_add_i32 s71, s71, s28
	s_mov_b32 m0, s71
	ds_read_b128 v[212:215], v228 offset:16384
	ds_read_b128 v[216:219], v228 offset:17408
	ds_read_b128 v[220:223], v228 offset:18432
	ds_read_b128 v[224:227], v228 offset:19456
	global_load_lds_dwordx4 v138, s[54:55]
	s_add_i32 m0, s71, 0x2000
	s_nop 0
	global_load_lds_dwordx4 v140, s[54:55]
	s_barrier
; #define PG8_STAGE(bufoff, gbase, voff) do { _Pragma("unroll") for (int _i = 0; _i < 2; ++_i) \
;         __builtin_amdgcn_global_load_lds((const unsigned*)((const char*)(gbase) + (voff)[_i]), (LAS unsigned*)(lds + (bufoff) + ldsw + _i * 8192), 16, 0, 0); } while (0)
; #define PG8_LDA(dst, b, h) do { _Pragma("unroll") for (int m = 0; m < 4; ++m) _Pragma("unroll") for (int k = 0; k < 2; ++k) dst[m][k] = *(const LAS bf16x8*)(lds + PG8_SA(b, h) + aoff + m * 2048 + k * 1024); } while (0)
; #define PG8_LDB(dst, b, h) do { _Pragma("unroll") for (int n = 0; n < 2; ++n) _Pragma("unroll") for (int k = 0; k < 2; ++k) dst[n][k] = *(const LAS bf16x8*)(lds + PG8_SB(b, h) + boff + n * 2048 + k * 1024); } while (0)
; #define PG8_MMA(ai, bj, At, Bt) do { __builtin_amdgcn_s_setprio(1); _Pragma("unroll") for (int m = 0; m < 4; ++m) _Pragma("unroll") for (int n = 0; n < 2; ++n) _Pragma("unroll") for (int k = 0; k < 2; ++k) \
;         acc[ai][bj][m][n] = __builtin_amdgcn_mfma_f32_16x16x32_bf16(Bt[n][k], At[m][k], acc[ai][bj][m][n], 0, 0, 0); __builtin_amdgcn_s_setprio(0); } while (0)
; #define PG8_WAIT_V(n) asm volatile("s_waitcnt vmcnt(" #n ")" ::: "memory")
; #define PG8_WAIT_L(n) asm volatile("s_waitcnt lgkmcnt(" #n ")" ::: "memory")
; #define PG8_BAR __builtin_amdgcn_s_barrier()
; #define PG8_SCHED __builtin_amdgcn_sched_barrier(0)
; template <class Epi, class Sched, int LD>
; __device__ __forceinline__ void gemm_phase(LAS unsigned char* lds, const Gemm g, const Sched& S, const Epi& E) {
;     ...
;             PG8_BAR; PG8_WAIT_L(0); PG8_MMA(0, 1, At, B1); PG8_BAR;
;             PG8_LDA(At, 0, 1); PG8_STAGE(PG8_SA(0, 0), a2, voffA);
;             PG8_BAR; PG8_WAIT_L(0); PG8_MMA(1, 0, At, B0); PG8_BAR; PG8_SCHED;
;             PG8_STAGE(PG8_SB(0, 1), b2 + hstep, voffB);
;             PG8_WAIT_V(6); PG8_BAR; PG8_MMA(1, 1, At, B1); PG8_BAR;
;             PG8_LDB(B0, 1, 0); PG8_SCHED; PG8_LDA(At, 1, 0); PG8_STAGE(PG8_SA(0, 1), a2 + hstep, voffA);
;             PG8_WAIT_L(8); PG8_BAR; PG8_WAIT_L(0); PG8_MMA(0, 0, At, B0); PG8_BAR; PG8_SCHED;
;             PG8_LDB(B1, 1, 1); PG8_STAGE(PG8_SB(1, 0), b3, voffB);
;             PG8_BAR; PG8_WAIT_L(0); PG8_MMA(0, 1, At, B1); PG8_BAR;
;             PG8_LDA(At, 1, 1); PG8_STAGE(PG8_SA(1, 0), a3, voffA);
;             PG8_BAR; PG8_WAIT_L(0); PG8_MMA(1, 0, At, B0); PG8_BAR; PG8_SCHED;
	s_waitcnt lgkmcnt(0)
	s_setprio 0
	v_mfma_f32_16x16x32_bf16 v[124:127], v[212:215], v[180:183], v[124:127]
	v_mfma_f32_16x16x32_bf16 v[116:119], v[220:223], v[180:183], v[116:119]
	v_mfma_f32_16x16x32_bf16 v[108:111], v[212:215], v[188:191], v[108:111]
	v_mfma_f32_16x16x32_bf16 v[100:103], v[220:223], v[188:191], v[100:103]
	v_mfma_f32_16x16x32_bf16 v[92:95], v[212:215], v[196:199], v[92:95]
	v_mfma_f32_16x16x32_bf16 v[84:87], v[220:223], v[196:199], v[84:87]
	v_mfma_f32_16x16x32_bf16 v[76:79], v[212:215], v[204:207], v[76:79]
	v_mfma_f32_16x16x32_bf16 v[68:71], v[220:223], v[204:207], v[68:71]
	v_mfma_f32_16x16x32_bf16 v[124:127], v[216:219], v[184:187], v[124:127]
	v_mfma_f32_16x16x32_bf16 v[116:119], v[224:227], v[184:187], v[116:119]
	v_mfma_f32_16x16x32_bf16 v[108:111], v[216:219], v[192:195], v[108:111]
	v_mfma_f32_16x16x32_bf16 v[100:103], v[224:227], v[192:195], v[100:103]
	v_mfma_f32_16x16x32_bf16 v[92:95], v[216:219], v[200:203], v[92:95]
	v_mfma_f32_16x16x32_bf16 v[84:87], v[224:227], v[200:203], v[84:87]
	v_mfma_f32_16x16x32_bf16 v[76:79], v[216:219], v[208:211], v[76:79]
	v_mfma_f32_16x16x32_bf16 v[68:71], v[224:227], v[208:211], v[68:71]
	s_setprio 2
	s_mov_b32 m0, s29
	s_barrier
	ds_read_b128 v[180:183], v144 offset:16384
	ds_read_b128 v[184:187], v144 offset:17408
	ds_read_b128 v[188:191], v144 offset:18432
	ds_read_b128 v[192:195], v144 offset:19456
	ds_read_b128 v[196:199], v144 offset:20480
	ds_read_b128 v[200:203], v144 offset:21504
	ds_read_b128 v[204:207], v144 offset:22528
	ds_read_b128 v[208:211], v144 offset:23552
	global_load_lds_dwordx4 v138, s[4:5]
	s_mov_b32 m0, s39
	s_nop 0
	global_load_lds_dwordx4 v140, s[4:5]
	s_waitcnt vmcnt(10)
	s_barrier
	s_waitcnt lgkmcnt(0)
	s_setprio 0
	v_mfma_f32_16x16x32_bf16 v[64:67], v[146:149], v[180:183], v[64:67]
	v_mfma_f32_16x16x32_bf16 v[56:59], v[154:157], v[180:183], v[56:59]
	v_mfma_f32_16x16x32_bf16 v[48:51], v[146:149], v[188:191], v[48:51]
	v_mfma_f32_16x16x32_bf16 v[40:43], v[154:157], v[188:191], v[40:43]
	v_mfma_f32_16x16x32_bf16 v[32:35], v[146:149], v[196:199], v[32:35]
	v_mfma_f32_16x16x32_bf16 v[24:27], v[154:157], v[196:199], v[24:27]
	v_mfma_f32_16x16x32_bf16 v[16:19], v[146:149], v[204:207], v[16:19]
	v_mfma_f32_16x16x32_bf16 v[8:11], v[154:157], v[204:207], v[8:11]
	v_mfma_f32_16x16x32_bf16 v[64:67], v[150:153], v[184:187], v[64:67]
	v_mfma_f32_16x16x32_bf16 v[56:59], v[176:179], v[184:187], v[56:59]
	v_mfma_f32_16x16x32_bf16 v[48:51], v[150:153], v[192:195], v[48:51]
	v_mfma_f32_16x16x32_bf16 v[40:43], v[176:179], v[192:195], v[40:43]
	v_mfma_f32_16x16x32_bf16 v[32:35], v[150:153], v[200:203], v[32:35]
	v_mfma_f32_16x16x32_bf16 v[24:27], v[176:179], v[200:203], v[24:27]
	s_setprio 3
	s_barrier
	v_mfma_f32_16x16x32_bf16 v[16:19], v[150:153], v[208:211], v[16:19]
	v_mfma_f32_16x16x32_bf16 v[8:11], v[176:179], v[208:211], v[8:11]
	s_setprio 2
	ds_read_b128 v[146:149], v228 offset:32768
	ds_read_b128 v[150:153], v228 offset:33792
	ds_read_b128 v[154:157], v228 offset:34816
	ds_read_b128 v[176:179], v228 offset:35840
	s_add_u32 s72, s54, 0x4000
	s_addc_u32 s73, s55, 0
	s_add_i32 s71, s74, s28
	s_mov_b32 m0, s71
	s_nop 0
	global_load_lds_dwordx4 v138, s[72:73]
	s_add_i32 m0, s71, 0x2000
	s_nop 0
	global_load_lds_dwordx4 v140, s[72:73]
	s_waitcnt vmcnt(6)
	s_barrier
	s_setprio 0
	v_mfma_f32_16x16x32_bf16 v[60:63], v[212:215], v[180:183], v[60:63]
	v_mfma_f32_16x16x32_bf16 v[52:55], v[220:223], v[180:183], v[52:55]
	v_mfma_f32_16x16x32_bf16 v[44:47], v[212:215], v[188:191], v[44:47]
	v_mfma_f32_16x16x32_bf16 v[36:39], v[220:223], v[188:191], v[36:39]
	v_mfma_f32_16x16x32_bf16 v[28:31], v[212:215], v[196:199], v[28:31]
	v_mfma_f32_16x16x32_bf16 v[20:23], v[220:223], v[196:199], v[20:23]
	v_mfma_f32_16x16x32_bf16 v[12:15], v[212:215], v[204:207], v[12:15]
	v_mfma_f32_16x16x32_bf16 v[4:7], v[220:223], v[204:207], v[4:7]
	v_mfma_f32_16x16x32_bf16 v[60:63], v[216:219], v[184:187], v[60:63]
	v_mfma_f32_16x16x32_bf16 v[52:55], v[224:227], v[184:187], v[52:55]
	v_mfma_f32_16x16x32_bf16 v[44:47], v[216:219], v[192:195], v[44:47]
	v_mfma_f32_16x16x32_bf16 v[36:39], v[224:227], v[192:195], v[36:39]
	v_mfma_f32_16x16x32_bf16 v[28:31], v[216:219], v[200:203], v[28:31]
	v_mfma_f32_16x16x32_bf16 v[20:23], v[224:227], v[200:203], v[20:23]
	v_mfma_f32_16x16x32_bf16 v[12:15], v[216:219], v[208:211], v[12:15]
	v_mfma_f32_16x16x32_bf16 v[4:7], v[224:227], v[208:211], v[4:7]
	s_setprio 2
	s_add_i32 s71, 0, 0x18000
	s_barrier
	s_add_u32 s4, s4, 0x4000
	s_addc_u32 s5, s5, 0
	s_mov_b32 m0, s52
	ds_read_b128 v[180:183], v144 offset:32768
	ds_read_b128 v[184:187], v144 offset:33792
	ds_read_b128 v[188:191], v144 offset:34816
	ds_read_b128 v[192:195], v144 offset:35840
	ds_read_b128 v[196:199], v144 offset:36864
	ds_read_b128 v[200:203], v144 offset:37888
	ds_read_b128 v[204:207], v144 offset:38912
	ds_read_b128 v[208:211], v144 offset:39936
	global_load_lds_dwordx4 v138, s[4:5]
	s_mov_b32 m0, s53
	s_nop 0
	global_load_lds_dwordx4 v140, s[4:5]
	s_waitcnt lgkmcnt(8)
	s_barrier
	s_waitcnt lgkmcnt(0)
	s_setprio 0
	v_mfma_f32_16x16x32_bf16 v[128:131], v[146:149], v[180:183], v[128:131]
	v_mfma_f32_16x16x32_bf16 v[120:123], v[154:157], v[180:183], v[120:123]
	v_mfma_f32_16x16x32_bf16 v[112:115], v[146:149], v[188:191], v[112:115]
	v_mfma_f32_16x16x32_bf16 v[104:107], v[154:157], v[188:191], v[104:107]
	v_mfma_f32_16x16x32_bf16 v[96:99], v[146:149], v[196:199], v[96:99]
	v_mfma_f32_16x16x32_bf16 v[88:91], v[154:157], v[196:199], v[88:91]
	v_mfma_f32_16x16x32_bf16 v[80:83], v[146:149], v[204:207], v[80:83]
	v_mfma_f32_16x16x32_bf16 v[72:75], v[154:157], v[204:207], v[72:75]
	v_mfma_f32_16x16x32_bf16 v[128:131], v[150:153], v[184:187], v[128:131]
	v_mfma_f32_16x16x32_bf16 v[120:123], v[176:179], v[184:187], v[120:123]
	v_mfma_f32_16x16x32_bf16 v[112:115], v[150:153], v[192:195], v[112:115]
	v_mfma_f32_16x16x32_bf16 v[104:107], v[176:179], v[192:195], v[104:107]
	v_mfma_f32_16x16x32_bf16 v[96:99], v[150:153], v[200:203], v[96:99]
	v_mfma_f32_16x16x32_bf16 v[88:91], v[176:179], v[200:203], v[88:91]
	s_setprio 3
	s_barrier
; #define PG8_STAGE(bufoff, gbase, voff) do { _Pragma("unroll") for (int _i = 0; _i < 2; ++_i) \
;         __builtin_amdgcn_global_load_lds((const unsigned*)((const char*)(gbase) + (voff)[_i]), (LAS unsigned*)(lds + (bufoff) + ldsw + _i * 8192), 16, 0, 0); } while (0)
; #define PG8_LDA(dst, b, h) do { _Pragma("unroll") for (int m = 0; m < 4; ++m) _Pragma("unroll") for (int k = 0; k < 2; ++k) dst[m][k] = *(const LAS bf16x8*)(lds + PG8_SA(b, h) + aoff + m * 2048 + k * 1024); } while (0)
; #define PG8_LDB(dst, b, h) do { _Pragma("unroll") for (int n = 0; n < 2; ++n) _Pragma("unroll") for (int k = 0; k < 2; ++k) dst[n][k] = *(const LAS bf16x8*)(lds + PG8_SB(b, h) + boff + n * 2048 + k * 1024); } while (0)
; #define PG8_MMA(ai, bj, At, Bt) do { __builtin_amdgcn_s_setprio(1); _Pragma("unroll") for (int m = 0; m < 4; ++m) _Pragma("unroll") for (int n = 0; n < 2; ++n) _Pragma("unroll") for (int k = 0; k < 2; ++k) \
;         acc[ai][bj][m][n] = __builtin_amdgcn_mfma_f32_16x16x32_bf16(Bt[n][k], At[m][k], acc[ai][bj][m][n], 0, 0, 0); __builtin_amdgcn_s_setprio(0); } while (0)
; #define PG8_WAIT_V(n) asm volatile("s_waitcnt vmcnt(" #n ")" ::: "memory")
; #define PG8_WAIT_L(n) asm volatile("s_waitcnt lgkmcnt(" #n ")" ::: "memory")
; #define PG8_BAR __builtin_amdgcn_s_barrier()
; #define PG8_SCHED __builtin_amdgcn_sched_barrier(0)
; template <class Epi, class Sched, int LD>
; __device__ __forceinline__ void gemm_phase(LAS unsigned char* lds, const Gemm g, const Sched& S, const Epi& E) {
;     ...
;             PG8_WAIT_L(8); PG8_BAR; PG8_WAIT_L(0); PG8_MMA(0, 0, At, B0); PG8_BAR; PG8_SCHED;
;             PG8_LDB(B1, 1, 1); PG8_STAGE(PG8_SB(1, 0), b3, voffB);
;             PG8_BAR; PG8_WAIT_L(0); PG8_MMA(0, 1, At, B1); PG8_BAR;
;             PG8_LDA(At, 1, 1); PG8_STAGE(PG8_SA(1, 0), a3, voffA);
;             PG8_BAR; PG8_WAIT_L(0); PG8_MMA(1, 0, At, B0); PG8_BAR; PG8_SCHED;
;             PG8_STAGE(PG8_SB(1, 1), b3 + hstep, voffB);
;             PG8_WAIT_V(6); PG8_BAR; PG8_MMA(1, 1, At, B1); PG8_BAR;
;         }
	v_mfma_f32_16x16x32_bf16 v[80:83], v[150:153], v[208:211], v[80:83]
	v_mfma_f32_16x16x32_bf16 v[72:75], v[176:179], v[208:211], v[72:75]
	s_setprio 2
	s_add_i32 s72, 0, 0x1c000
	s_add_u32 s4, s54, 0x8000
	s_addc_u32 s5, s55, 0
	s_add_i32 s71, s71, s28
	s_mov_b32 m0, s71
	ds_read_b128 v[212:215], v228 offset:49152
	ds_read_b128 v[216:219], v228 offset:50176
	ds_read_b128 v[220:223], v228 offset:51200
	ds_read_b128 v[224:227], v228 offset:52224
	global_load_lds_dwordx4 v138, s[4:5]
	s_add_i32 m0, s71, 0x2000
	s_nop 0
	global_load_lds_dwordx4 v140, s[4:5]
	s_barrier
	s_waitcnt lgkmcnt(0)
	s_setprio 0
	v_mfma_f32_16x16x32_bf16 v[124:127], v[212:215], v[180:183], v[124:127]
	v_mfma_f32_16x16x32_bf16 v[116:119], v[220:223], v[180:183], v[116:119]
	v_mfma_f32_16x16x32_bf16 v[108:111], v[212:215], v[188:191], v[108:111]
	v_mfma_f32_16x16x32_bf16 v[100:103], v[220:223], v[188:191], v[100:103]
	v_mfma_f32_16x16x32_bf16 v[92:95], v[212:215], v[196:199], v[92:95]
	v_mfma_f32_16x16x32_bf16 v[84:87], v[220:223], v[196:199], v[84:87]
	v_mfma_f32_16x16x32_bf16 v[76:79], v[212:215], v[204:207], v[76:79]
	v_mfma_f32_16x16x32_bf16 v[68:71], v[220:223], v[204:207], v[68:71]
	v_mfma_f32_16x16x32_bf16 v[124:127], v[216:219], v[184:187], v[124:127]
	v_mfma_f32_16x16x32_bf16 v[116:119], v[224:227], v[184:187], v[116:119]
	v_mfma_f32_16x16x32_bf16 v[108:111], v[216:219], v[192:195], v[108:111]
	v_mfma_f32_16x16x32_bf16 v[100:103], v[224:227], v[192:195], v[100:103]
	v_mfma_f32_16x16x32_bf16 v[92:95], v[216:219], v[200:203], v[92:95]
	v_mfma_f32_16x16x32_bf16 v[84:87], v[224:227], v[200:203], v[84:87]
	v_mfma_f32_16x16x32_bf16 v[76:79], v[216:219], v[208:211], v[76:79]
	v_mfma_f32_16x16x32_bf16 v[68:71], v[224:227], v[208:211], v[68:71]
	s_setprio 2
	s_mov_b32 m0, s60
	s_barrier
	ds_read_b128 v[180:183], v144 offset:49152
	ds_read_b128 v[184:187], v144 offset:50176
	ds_read_b128 v[188:191], v144 offset:51200
	ds_read_b128 v[192:195], v144 offset:52224
	ds_read_b128 v[196:199], v144 offset:53248
	ds_read_b128 v[200:203], v144 offset:54272
	ds_read_b128 v[204:207], v144 offset:55296
	ds_read_b128 v[208:211], v144 offset:56320
	global_load_lds_dwordx4 v138, s[56:57]
	s_mov_b32 m0, s61
	s_nop 0
	global_load_lds_dwordx4 v140, s[56:57]
	s_waitcnt vmcnt(10)
	s_barrier
	s_waitcnt lgkmcnt(0)
	s_setprio 0
	v_mfma_f32_16x16x32_bf16 v[64:67], v[146:149], v[180:183], v[64:67]
	v_mfma_f32_16x16x32_bf16 v[56:59], v[154:157], v[180:183], v[56:59]
	v_mfma_f32_16x16x32_bf16 v[48:51], v[146:149], v[188:191], v[48:51]
	v_mfma_f32_16x16x32_bf16 v[40:43], v[154:157], v[188:191], v[40:43]
	v_mfma_f32_16x16x32_bf16 v[32:35], v[146:149], v[196:199], v[32:35]
	v_mfma_f32_16x16x32_bf16 v[24:27], v[154:157], v[196:199], v[24:27]
	v_mfma_f32_16x16x32_bf16 v[16:19], v[146:149], v[204:207], v[16:19]
	v_mfma_f32_16x16x32_bf16 v[8:11], v[154:157], v[204:207], v[8:11]
	v_mfma_f32_16x16x32_bf16 v[64:67], v[150:153], v[184:187], v[64:67]
	v_mfma_f32_16x16x32_bf16 v[56:59], v[176:179], v[184:187], v[56:59]
	v_mfma_f32_16x16x32_bf16 v[48:51], v[150:153], v[192:195], v[48:51]
	v_mfma_f32_16x16x32_bf16 v[40:43], v[176:179], v[192:195], v[40:43]
	v_mfma_f32_16x16x32_bf16 v[32:35], v[150:153], v[200:203], v[32:35]
	v_mfma_f32_16x16x32_bf16 v[24:27], v[176:179], v[200:203], v[24:27]
	s_setprio 3
	s_barrier
	v_mfma_f32_16x16x32_bf16 v[16:19], v[150:153], v[208:211], v[16:19]
	v_mfma_f32_16x16x32_bf16 v[8:11], v[176:179], v[208:211], v[8:11]
	s_setprio 2
	ds_read_b128 v[146:149], v228
	ds_read_b128 v[150:153], v228 offset:1024
	ds_read_b128 v[154:157], v228 offset:2048
	ds_read_b128 v[176:179], v228 offset:3072
	s_add_u32 s4, s54, 0xc000
	s_addc_u32 s5, s55, 0
	s_add_i32 s54, s72, s28
	s_mov_b32 m0, s54
	s_nop 0
	global_load_lds_dwordx4 v138, s[4:5]
	s_add_i32 m0, s54, 0x2000
	s_nop 0
	global_load_lds_dwordx4 v140, s[4:5]
	s_waitcnt vmcnt(6)
	s_barrier
	s_setprio 0
	v_mfma_f32_16x16x32_bf16 v[60:63], v[212:215], v[180:183], v[60:63]
	v_mfma_f32_16x16x32_bf16 v[52:55], v[220:223], v[180:183], v[52:55]
	v_mfma_f32_16x16x32_bf16 v[44:47], v[212:215], v[188:191], v[44:47]
	v_mfma_f32_16x16x32_bf16 v[36:39], v[220:223], v[188:191], v[36:39]
	v_mfma_f32_16x16x32_bf16 v[28:31], v[212:215], v[196:199], v[28:31]
	v_mfma_f32_16x16x32_bf16 v[20:23], v[220:223], v[196:199], v[20:23]
	v_mfma_f32_16x16x32_bf16 v[12:15], v[212:215], v[204:207], v[12:15]
	v_mfma_f32_16x16x32_bf16 v[4:7], v[220:223], v[204:207], v[4:7]
	v_mfma_f32_16x16x32_bf16 v[60:63], v[216:219], v[184:187], v[60:63]
	v_mfma_f32_16x16x32_bf16 v[52:55], v[224:227], v[184:187], v[52:55]
	v_mfma_f32_16x16x32_bf16 v[44:47], v[216:219], v[192:195], v[44:47]
	v_mfma_f32_16x16x32_bf16 v[36:39], v[224:227], v[192:195], v[36:39]
	v_mfma_f32_16x16x32_bf16 v[28:31], v[216:219], v[200:203], v[28:31]
	v_mfma_f32_16x16x32_bf16 v[20:23], v[224:227], v[200:203], v[20:23]
	v_mfma_f32_16x16x32_bf16 v[12:15], v[216:219], v[208:211], v[12:15]
	v_mfma_f32_16x16x32_bf16 v[4:7], v[224:227], v[208:211], v[4:7]
	s_setprio 2
	s_add_i32 s70, s70, 2
	s_add_u32 s50, s50, 0x10000
	s_addc_u32 s51, s51, 0
	s_add_u32 s45, s45, 0x10000
	s_addc_u32 s47, s47, 0
	s_cmp_gt_u32 s70, 29
	s_barrier
	s_cbranch_scc0 .LBB0_899
; __device__ __forceinline__ unsigned cvt_pk_bf16(float lo, float hi) { f32x2 v = {lo, hi}; bf16x2v b = __builtin_convertvector(v, bf16x2v); return __builtin_bit_cast(unsigned, b); }
; __device__ __forceinline__ float silu_f(float x) { return x * __builtin_amdgcn_rcpf(1.f + __expf(-x)); }
;     __device__ __forceinline__ void operator()(const f32x4 (&acc)[2][2][4][2], const Unit& u, int wr, int wc, int fr, int fq) const {
;         const int row0 = u.pm * BM + wr * 64 + fr, col0 = u.pn * 128 + wc * 32 + 8 * fq;
; #pragma unroll
;         for (int ai = 0; ai < 2; ++ai)
; #pragma unroll
;             for (int m = 0; m < 4; ++m) {
;                 bf16_t* rowp = O + img_off(row0 + ai * HALF + m * 16, col0, D_FF / 64);
;                 const f32x4 g0 = acc[ai][0][m][0], g1 = acc[ai][0][m][1], u0 = acc[ai][1][m][0], u1 = acc[ai][1][m][1];
;                 u32x4 w;
;                 w.x = cvt_pk_bf16(silu_f(g0[0]) * u0[0], silu_f(g0[1]) * u0[1]); w.y = cvt_pk_bf16(silu_f(g0[2]) * u0[2], silu_f(g0[3]) * u0[3]);
;                 w.z = cvt_pk_bf16(silu_f(g1[0]) * u1[0], silu_f(g1[1]) * u1[1]); w.w = cvt_pk_bf16(silu_f(g1[2]) * u1[2], silu_f(g1[3]) * u1[3]);
;                 *(u32x4*)rowp = w;
; template <class Epi, class Sched, int LD>
; __device__ __forceinline__ void gemm_phase(LAS unsigned char* lds, const Gemm g, const Sched& S, const Epi& E) {
;     ...
;         cur = nxt; cA = nA; cB = nB; ++ui;
	s_setprio 0
	v_mul_f32_e32 v148, 0xbfb8aa3b, v128
	v_mul_f32_e32 v149, 0xbfb8aa3b, v129
	v_exp_f32_e32 v148, v148
	v_exp_f32_e32 v149, v149
	s_lshl_b32 s5, s69, 8
	s_add_i32 s5, s5, s58
	v_add_f32_e32 v148, 1.0, v148
	v_add_f32_e32 v149, 1.0, v149
	v_rcp_f32_e32 v148, v148
	v_rcp_f32_e32 v149, v149
	s_lshl_b32 s4, s68, 7
	s_or_b32 s4, s4, s59
	s_ashr_i32 s45, s5, 8
	v_pk_mul_f32 v[128:129], v[128:129], v[148:149]
	s_ashr_i32 s4, s4, 6
	v_pk_mul_f32 v[124:125], v[128:129], v[124:125]
	s_mulk_i32 s45, 0x58
	v_cvt_pk_bf16_f32 v124, v124, v125
	v_mul_f32_e32 v125, 0xbfb8aa3b, v130
	v_exp_f32_e32 v125, v125
	s_add_i32 s50, s45, s4
	s_ashr_i32 s51, s50, 31
	s_lshl_b64 s[50:51], s[50:51], 15
	v_add_f32_e32 v125, 1.0, v125
	v_rcp_f32_e32 v128, v125
	v_mul_f32_e32 v125, 0xbfb8aa3b, v131
	v_exp_f32_e32 v125, v125
	s_add_u32 s45, s16, s50
	s_addc_u32 s47, s17, s51
	s_lshl_b32 s50, s5, 7
	v_add_f32_e32 v125, 1.0, v125
	v_rcp_f32_e32 v129, v125
	s_and_b32 s50, s50, 0x4000
	s_add_u32 s50, s45, s50
	s_addc_u32 s51, s47, 0
	v_pk_mul_f32 v[128:129], v[130:131], v[128:129]
	s_or_b32 s45, s5, 16
	v_pk_mul_f32 v[126:127], v[128:129], v[126:127]
	s_lshr_b32 s45, s45, 3
	v_cvt_pk_bf16_f32 v125, v126, v127
	v_mul_f32_e32 v126, 0xbfb8aa3b, v120
	v_mul_f32_e32 v127, 0xbfb8aa3b, v121
	v_exp_f32_e32 v126, v126
	v_exp_f32_e32 v127, v127
	v_or_b32_e32 v145, s5, v137
	s_and_b32 s45, s45, 10
	v_add_f32_e32 v126, 1.0, v126
	v_add_f32_e32 v127, 1.0, v127
	v_rcp_f32_e32 v126, v126
	v_rcp_f32_e32 v127, v127
	v_lshlrev_b32_e32 v132, 6, v145
	v_lshlrev_b32_e32 v146, 2, v145
	s_or_b32 s45, s45, s64
	v_pk_mul_f32 v[120:121], v[120:121], v[126:127]
	v_and_or_b32 v132, v132, s15, v142
	v_pk_mul_f32 v[116:117], v[120:121], v[116:117]
	v_and_b32_e32 v146, 32, v146
	v_cvt_pk_bf16_f32 v126, v116, v117
	v_mul_f32_e32 v116, 0xbfb8aa3b, v122
	v_mul_f32_e32 v117, 0xbfb8aa3b, v123
	v_exp_f32_e32 v116, v116
	v_exp_f32_e32 v117, v117
	s_lshl_b32 s45, s45, 10
	v_bitop3_b32 v147, v132, s65, v146 bitop3:0xde
	v_add_f32_e32 v116, 1.0, v116
	v_add_f32_e32 v117, 1.0, v117
	v_rcp_f32_e32 v116, v116
	v_rcp_f32_e32 v117, v117
	s_and_b64 vcc, exec, s[42:43]
	s_mov_b32 s68, s44
	s_mov_b32 s69, s46
	v_pk_mul_f32 v[116:117], v[122:123], v[116:117]
	s_mov_b64 s[54:55], s[40:41]
	v_pk_mul_f32 v[116:117], v[116:117], v[118:119]
	v_bitop3_b32 v118, v132, s45, v146 bitop3:0xde
	v_cvt_pk_bf16_f32 v127, v116, v117
	v_mul_f32_e32 v116, 0xbfb8aa3b, v112
	v_mul_f32_e32 v117, 0xbfb8aa3b, v113
	v_exp_f32_e32 v116, v116
	v_exp_f32_e32 v117, v117
	s_or_b32 s45, s5, 32
	s_or_b32 s5, s5, 48
	v_add_f32_e32 v116, 1.0, v116
	v_add_f32_e32 v117, 1.0, v117
	v_rcp_f32_e32 v116, v116
	v_rcp_f32_e32 v117, v117
	s_lshr_b32 s45, s45, 3
	s_lshr_b32 s5, s5, 3
	s_and_b32 s45, s45, 12
	v_pk_mul_f32 v[112:113], v[112:113], v[116:117]
	s_and_b32 s5, s5, 14
	v_pk_mul_f32 v[108:109], v[112:113], v[108:109]
	s_or_b32 s45, s45, s64
	v_cvt_pk_bf16_f32 v108, v108, v109
	v_mul_f32_e32 v109, 0xbfb8aa3b, v114
	v_exp_f32_e32 v109, v109
	s_or_b32 s5, s5, s64
	s_lshl_b32 s45, s45, 10
	s_lshl_b32 s5, s5, 10
	v_add_f32_e32 v109, 1.0, v109
	v_rcp_f32_e32 v112, v109
	v_mul_f32_e32 v109, 0xbfb8aa3b, v115
	v_exp_f32_e32 v109, v109
	global_store_dwordx4 v147, v[124:127], s[50:51]
	v_add_f32_e32 v109, 1.0, v109
	v_rcp_f32_e32 v113, v109
	s_nop 0
	v_pk_mul_f32 v[112:113], v[114:115], v[112:113]
	s_nop 0
	v_pk_mul_f32 v[110:111], v[112:113], v[110:111]
	s_nop 0
	v_cvt_pk_bf16_f32 v109, v110, v111
	v_mul_f32_e32 v110, 0xbfb8aa3b, v104
	v_mul_f32_e32 v111, 0xbfb8aa3b, v105
	v_exp_f32_e32 v110, v110
	v_exp_f32_e32 v111, v111
	v_add_f32_e32 v110, 1.0, v110
	v_add_f32_e32 v111, 1.0, v111
	v_rcp_f32_e32 v110, v110
	v_rcp_f32_e32 v111, v111
	s_nop 0
	v_pk_mul_f32 v[104:105], v[104:105], v[110:111]
	s_nop 0
	v_pk_mul_f32 v[100:101], v[104:105], v[100:101]
	s_nop 0
	v_cvt_pk_bf16_f32 v110, v100, v101
	v_mul_f32_e32 v100, 0xbfb8aa3b, v106
	v_mul_f32_e32 v101, 0xbfb8aa3b, v107
	v_exp_f32_e32 v100, v100
	v_exp_f32_e32 v101, v101
	v_add_f32_e32 v100, 1.0, v100
	v_add_f32_e32 v101, 1.0, v101
	v_rcp_f32_e32 v100, v100
	v_rcp_f32_e32 v101, v101
	s_nop 0
	v_pk_mul_f32 v[100:101], v[106:107], v[100:101]
	s_nop 0
	v_pk_mul_f32 v[100:101], v[100:101], v[102:103]
	v_bitop3_b32 v102, v132, s45, v146 bitop3:0xde
	v_cvt_pk_bf16_f32 v111, v100, v101
	v_mul_f32_e32 v100, 0xbfb8aa3b, v96
	v_mul_f32_e32 v101, 0xbfb8aa3b, v97
	v_exp_f32_e32 v100, v100
	v_exp_f32_e32 v101, v101
	global_store_dwordx4 v118, v[108:111], s[50:51]
	v_add_f32_e32 v100, 1.0, v100
	v_add_f32_e32 v101, 1.0, v101
	v_rcp_f32_e32 v100, v100
	v_rcp_f32_e32 v101, v101
	s_nop 0
	v_pk_mul_f32 v[96:97], v[96:97], v[100:101]
	s_nop 0
	v_pk_mul_f32 v[92:93], v[96:97], v[92:93]
	s_nop 0
	v_cvt_pk_bf16_f32 v92, v92, v93
	v_mul_f32_e32 v93, 0xbfb8aa3b, v98
	v_exp_f32_e32 v93, v93
	s_nop 0
	v_add_f32_e32 v93, 1.0, v93
	v_rcp_f32_e32 v96, v93
	v_mul_f32_e32 v93, 0xbfb8aa3b, v99
	v_exp_f32_e32 v93, v93
	s_nop 0
	v_add_f32_e32 v93, 1.0, v93
	v_rcp_f32_e32 v97, v93
	s_nop 0
	v_pk_mul_f32 v[96:97], v[98:99], v[96:97]
	s_nop 0
	v_pk_mul_f32 v[94:95], v[96:97], v[94:95]
	s_nop 0
	v_cvt_pk_bf16_f32 v93, v94, v95
	v_mul_f32_e32 v94, 0xbfb8aa3b, v88
	v_mul_f32_e32 v95, 0xbfb8aa3b, v89
	v_exp_f32_e32 v94, v94
	v_exp_f32_e32 v95, v95
	v_add_f32_e32 v94, 1.0, v94
	v_add_f32_e32 v95, 1.0, v95
	v_rcp_f32_e32 v94, v94
	v_rcp_f32_e32 v95, v95
	s_nop 0
	v_pk_mul_f32 v[88:89], v[88:89], v[94:95]
	s_nop 0
	v_pk_mul_f32 v[84:85], v[88:89], v[84:85]
	s_nop 0
	v_cvt_pk_bf16_f32 v94, v84, v85
	v_mul_f32_e32 v84, 0xbfb8aa3b, v90
	v_mul_f32_e32 v85, 0xbfb8aa3b, v91
	v_exp_f32_e32 v84, v84
	v_exp_f32_e32 v85, v85
	v_add_f32_e32 v84, 1.0, v84
; __device__ __forceinline__ unsigned cvt_pk_bf16(float lo, float hi) { f32x2 v = {lo, hi}; bf16x2v b = __builtin_convertvector(v, bf16x2v); return __builtin_bit_cast(unsigned, b); }
; __device__ __forceinline__ float silu_f(float x) { return x * __builtin_amdgcn_rcpf(1.f + __expf(-x)); }
;     __device__ __forceinline__ void operator()(const f32x4 (&acc)[2][2][4][2], const Unit& u, int wr, int wc, int fr, int fq) const {
;     ...
;             for (int m = 0; m < 4; ++m) {
;                 bf16_t* rowp = O + img_off(row0 + ai * HALF + m * 16, col0, D_FF / 64);
;                 const f32x4 g0 = acc[ai][0][m][0], g1 = acc[ai][0][m][1], u0 = acc[ai][1][m][0], u1 = acc[ai][1][m][1];
;                 u32x4 w;
;                 w.x = cvt_pk_bf16(silu_f(g0[0]) * u0[0], silu_f(g0[1]) * u0[1]); w.y = cvt_pk_bf16(silu_f(g0[2]) * u0[2], silu_f(g0[3]) * u0[3]);
;                 w.z = cvt_pk_bf16(silu_f(g1[0]) * u1[0], silu_f(g1[1]) * u1[1]); w.w = cvt_pk_bf16(silu_f(g1[2]) * u1[2], silu_f(g1[3]) * u1[3]);
;                 *(u32x4*)rowp = w;
	v_add_f32_e32 v85, 1.0, v85
	v_rcp_f32_e32 v84, v84
	v_rcp_f32_e32 v85, v85
	s_nop 0
	v_pk_mul_f32 v[84:85], v[90:91], v[84:85]
	s_nop 0
	v_pk_mul_f32 v[84:85], v[84:85], v[86:87]
	v_bitop3_b32 v86, v132, s5, v146 bitop3:0xde
	v_cvt_pk_bf16_f32 v95, v84, v85
	v_mul_f32_e32 v84, 0xbfb8aa3b, v80
	v_mul_f32_e32 v85, 0xbfb8aa3b, v81
	v_exp_f32_e32 v84, v84
	v_exp_f32_e32 v85, v85
	global_store_dwordx4 v102, v[92:95], s[50:51]
	v_add_f32_e32 v84, 1.0, v84
	v_add_f32_e32 v85, 1.0, v85
	v_rcp_f32_e32 v84, v84
	v_rcp_f32_e32 v85, v85
	s_nop 0
	v_pk_mul_f32 v[80:81], v[80:81], v[84:85]
	s_nop 0
	v_pk_mul_f32 v[76:77], v[80:81], v[76:77]
	s_nop 0
	v_cvt_pk_bf16_f32 v76, v76, v77
	v_mul_f32_e32 v77, 0xbfb8aa3b, v82
	v_exp_f32_e32 v77, v77
	s_nop 0
	v_add_f32_e32 v77, 1.0, v77
	v_rcp_f32_e32 v80, v77
	v_mul_f32_e32 v77, 0xbfb8aa3b, v83
	v_exp_f32_e32 v77, v77
	s_nop 0
	v_add_f32_e32 v77, 1.0, v77
	v_rcp_f32_e32 v81, v77
	s_nop 0
	v_pk_mul_f32 v[80:81], v[82:83], v[80:81]
	s_nop 0
	v_pk_mul_f32 v[78:79], v[80:81], v[78:79]
	s_nop 0
	v_cvt_pk_bf16_f32 v77, v78, v79
	v_mul_f32_e32 v78, 0xbfb8aa3b, v72
	v_mul_f32_e32 v79, 0xbfb8aa3b, v73
	v_exp_f32_e32 v78, v78
	v_exp_f32_e32 v79, v79
	v_add_f32_e32 v78, 1.0, v78
	v_add_f32_e32 v79, 1.0, v79
	v_rcp_f32_e32 v78, v78
	v_rcp_f32_e32 v79, v79
	s_nop 0
	v_pk_mul_f32 v[72:73], v[72:73], v[78:79]
	s_nop 0
	v_pk_mul_f32 v[68:69], v[72:73], v[68:69]
	v_mul_f32_e32 v73, 0xbfb8aa3b, v65
	v_cvt_pk_bf16_f32 v78, v68, v69
	v_mul_f32_e32 v68, 0xbfb8aa3b, v74
	v_mul_f32_e32 v69, 0xbfb8aa3b, v75
	v_exp_f32_e32 v68, v68
	v_exp_f32_e32 v69, v69
	v_exp_f32_e32 v73, v73
	v_add_f32_e32 v68, 1.0, v68
	v_add_f32_e32 v69, 1.0, v69
	v_rcp_f32_e32 v68, v68
	v_rcp_f32_e32 v69, v69
	v_add_f32_e32 v73, 1.0, v73
	v_rcp_f32_e32 v73, v73
	v_pk_mul_f32 v[68:69], v[74:75], v[68:69]
	s_nop 0
	v_pk_mul_f32 v[68:69], v[68:69], v[70:71]
	v_add_u32_e32 v70, 0x80, v145
	v_lshlrev_b32_e32 v71, 6, v70
	v_lshlrev_b32_e32 v72, 2, v70
	v_and_or_b32 v71, v71, s15, v142
	v_and_b32_e32 v72, 32, v72
	v_bitop3_b32 v132, v71, s65, v72 bitop3:0xde
	v_mul_f32_e32 v72, 0xbfb8aa3b, v64
	v_exp_f32_e32 v72, v72
	v_cvt_pk_bf16_f32 v79, v68, v69
	v_lshrrev_b32_e32 v68, 8, v70
	v_mov_b32_e32 v69, s4
	v_add_f32_e32 v72, 1.0, v72
	v_rcp_f32_e32 v72, v72
	s_movk_i32 s4, 0x58
	v_mad_i32_i24 v68, v68, s4, v69
	v_ashrrev_i32_e32 v69, 31, v68
	v_pk_mul_f32 v[64:65], v[64:65], v[72:73]
	v_lshlrev_b64 v[68:69], 15, v[68:69]
	v_pk_mul_f32 v[60:61], v[64:65], v[60:61]
	v_lshlrev_b32_e32 v70, 7, v70
	v_cvt_pk_bf16_f32 v60, v60, v61
	v_mul_f32_e32 v61, 0xbfb8aa3b, v66
	v_exp_f32_e32 v61, v61
	v_lshl_add_u64 v[68:69], s[16:17], 0, v[68:69]
	v_and_b32_e32 v70, 0x4000, v70
	v_mov_b32_e32 v71, v133
	v_add_f32_e32 v61, 1.0, v61
	v_rcp_f32_e32 v64, v61
	v_mul_f32_e32 v61, 0xbfb8aa3b, v67
	v_exp_f32_e32 v61, v61
	v_lshl_add_u64 v[70:71], v[68:69], 0, v[70:71]
	v_lshl_add_u64 v[70:71], v[70:71], 0, v[132:133]
	s_mov_b64 s[4:5], s[48:49]
	v_add_f32_e32 v61, 1.0, v61
	v_rcp_f32_e32 v65, v61
	global_store_dwordx4 v86, v[76:79], s[50:51]
	v_pk_mul_f32 v[64:65], v[66:67], v[64:65]
	s_nop 0
	v_pk_mul_f32 v[62:63], v[64:65], v[62:63]
	s_nop 0
	v_cvt_pk_bf16_f32 v61, v62, v63
	v_mul_f32_e32 v62, 0xbfb8aa3b, v56
	v_mul_f32_e32 v63, 0xbfb8aa3b, v57
	v_exp_f32_e32 v62, v62
	v_exp_f32_e32 v63, v63
	v_add_f32_e32 v62, 1.0, v62
	v_add_f32_e32 v63, 1.0, v63
	v_rcp_f32_e32 v62, v62
	v_rcp_f32_e32 v63, v63
	s_nop 0
	v_pk_mul_f32 v[56:57], v[56:57], v[62:63]
	s_nop 0
	v_pk_mul_f32 v[52:53], v[56:57], v[52:53]
	s_nop 0
	v_cvt_pk_bf16_f32 v62, v52, v53
	v_mul_f32_e32 v52, 0xbfb8aa3b, v58
	v_mul_f32_e32 v53, 0xbfb8aa3b, v59
	v_exp_f32_e32 v52, v52
	v_exp_f32_e32 v53, v53
	v_add_f32_e32 v52, 1.0, v52
	v_add_f32_e32 v53, 1.0, v53
	v_rcp_f32_e32 v52, v52
	v_rcp_f32_e32 v53, v53
	s_nop 0
	v_pk_mul_f32 v[52:53], v[58:59], v[52:53]
	s_nop 0
	v_pk_mul_f32 v[52:53], v[52:53], v[54:55]
	s_nop 0
	v_cvt_pk_bf16_f32 v63, v52, v53
	v_add_u32_e32 v52, 0x90, v145
	v_lshrrev_b32_e32 v54, 3, v52
	v_lshlrev_b32_e32 v53, 6, v52
	v_and_or_b32 v54, v54, 10, s64
	v_lshlrev_b32_e32 v55, 2, v52
	v_and_or_b32 v53, v53, s15, v142
	v_lshlrev_b32_e32 v54, 10, v54
	v_and_b32_e32 v55, 32, v55
	v_bitop3_b32 v132, v53, v54, v55 bitop3:0xde
	v_mul_f32_e32 v54, 0xbfb8aa3b, v48
	v_mul_f32_e32 v55, 0xbfb8aa3b, v49
	v_exp_f32_e32 v54, v54
	v_exp_f32_e32 v55, v55
	v_lshlrev_b32_e32 v52, 7, v52
	v_and_b32_e32 v52, 0x4000, v52
	v_add_f32_e32 v54, 1.0, v54
	v_add_f32_e32 v55, 1.0, v55
	v_rcp_f32_e32 v54, v54
	v_rcp_f32_e32 v55, v55
	v_mov_b32_e32 v53, v133
	v_lshl_add_u64 v[52:53], v[68:69], 0, v[52:53]
	v_lshl_add_u64 v[52:53], v[52:53], 0, v[132:133]
	v_pk_mul_f32 v[48:49], v[48:49], v[54:55]
	global_store_dwordx4 v[70:71], v[60:63], off
	v_pk_mul_f32 v[44:45], v[48:49], v[44:45]
	s_nop 0
	v_cvt_pk_bf16_f32 v44, v44, v45
	v_mul_f32_e32 v45, 0xbfb8aa3b, v50
	v_exp_f32_e32 v45, v45
	s_nop 0
	v_add_f32_e32 v45, 1.0, v45
	v_rcp_f32_e32 v48, v45
	v_mul_f32_e32 v45, 0xbfb8aa3b, v51
	v_exp_f32_e32 v45, v45
	s_nop 0
	v_add_f32_e32 v45, 1.0, v45
	v_rcp_f32_e32 v49, v45
; __device__ __forceinline__ unsigned cvt_pk_bf16(float lo, float hi) { f32x2 v = {lo, hi}; bf16x2v b = __builtin_convertvector(v, bf16x2v); return __builtin_bit_cast(unsigned, b); }
; __device__ __forceinline__ float silu_f(float x) { return x * __builtin_amdgcn_rcpf(1.f + __expf(-x)); }
; #define PG8_WAIT_V(n) asm volatile("s_waitcnt vmcnt(" #n ")" ::: "memory")
; #define PG8_BAR __builtin_amdgcn_s_barrier()
;     __device__ __forceinline__ void operator()(const f32x4 (&acc)[2][2][4][2], const Unit& u, int wr, int wc, int fr, int fq) const {
;     ...
;             for (int m = 0; m < 4; ++m) {
;                 bf16_t* rowp = O + img_off(row0 + ai * HALF + m * 16, col0, D_FF / 64);
;                 const f32x4 g0 = acc[ai][0][m][0], g1 = acc[ai][0][m][1], u0 = acc[ai][1][m][0], u1 = acc[ai][1][m][1];
;                 u32x4 w;
;                 w.x = cvt_pk_bf16(silu_f(g0[0]) * u0[0], silu_f(g0[1]) * u0[1]); w.y = cvt_pk_bf16(silu_f(g0[2]) * u0[2], silu_f(g0[3]) * u0[3]);
;                 w.z = cvt_pk_bf16(silu_f(g1[0]) * u1[0], silu_f(g1[1]) * u1[1]); w.w = cvt_pk_bf16(silu_f(g1[2]) * u1[2], silu_f(g1[3]) * u1[3]);
;                 *(u32x4*)rowp = w;
; template <class Epi, class Sched, int LD>
; __device__ __forceinline__ void gemm_phase(LAS unsigned char* lds, const Gemm g, const Sched& S, const Epi& E) {
;     ...
;         if (!has_next) break;
; #pragma unroll
;         for (int a = 0; a < 2; ++a)
; #pragma unroll
;             for (int b = 0; b < 2; ++b)
; #pragma unroll
;                 for (int m = 0; m < 4; ++m)
; #pragma unroll
;                     for (int n = 0; n < 2; ++n) acc[a][b][m][n] = (f32x4){0.f, 0.f, 0.f, 0.f};
;         cur = nxt; cA = nA; cB = nB; ++ui;
;     }
;     PG8_WAIT_V(0);
;     if (wr == 0) PG8_BAR;
;     PG8_BAR;
	s_nop 0
	v_pk_mul_f32 v[48:49], v[50:51], v[48:49]
	s_nop 0
	v_pk_mul_f32 v[46:47], v[48:49], v[46:47]
	s_nop 0
	v_cvt_pk_bf16_f32 v45, v46, v47
	v_mul_f32_e32 v46, 0xbfb8aa3b, v40
	v_mul_f32_e32 v47, 0xbfb8aa3b, v41
	v_exp_f32_e32 v46, v46
	v_exp_f32_e32 v47, v47
	v_add_f32_e32 v46, 1.0, v46
	v_add_f32_e32 v47, 1.0, v47
	v_rcp_f32_e32 v46, v46
	v_rcp_f32_e32 v47, v47
	s_nop 0
	v_pk_mul_f32 v[40:41], v[40:41], v[46:47]
	s_nop 0
	v_pk_mul_f32 v[36:37], v[40:41], v[36:37]
	s_nop 0
	v_cvt_pk_bf16_f32 v46, v36, v37
	v_mul_f32_e32 v36, 0xbfb8aa3b, v42
	v_mul_f32_e32 v37, 0xbfb8aa3b, v43
	v_exp_f32_e32 v36, v36
	v_exp_f32_e32 v37, v37
	v_add_f32_e32 v36, 1.0, v36
	v_add_f32_e32 v37, 1.0, v37
	v_rcp_f32_e32 v36, v36
	v_rcp_f32_e32 v37, v37
	s_nop 0
	v_pk_mul_f32 v[36:37], v[42:43], v[36:37]
	s_nop 0
	v_pk_mul_f32 v[36:37], v[36:37], v[38:39]
	s_nop 0
	v_cvt_pk_bf16_f32 v47, v36, v37
	v_add_u32_e32 v36, 0xa0, v145
	v_lshrrev_b32_e32 v38, 3, v36
	v_lshlrev_b32_e32 v37, 6, v36
	v_and_or_b32 v38, v38, 12, s64
	v_lshlrev_b32_e32 v39, 2, v36
	v_and_or_b32 v37, v37, s15, v142
	v_lshlrev_b32_e32 v38, 10, v38
	v_and_b32_e32 v39, 32, v39
	v_bitop3_b32 v132, v37, v38, v39 bitop3:0xde
	v_mul_f32_e32 v38, 0xbfb8aa3b, v32
	v_mul_f32_e32 v39, 0xbfb8aa3b, v33
	v_exp_f32_e32 v38, v38
	v_exp_f32_e32 v39, v39
	v_lshlrev_b32_e32 v36, 7, v36
	v_and_b32_e32 v36, 0x4000, v36
	v_add_f32_e32 v38, 1.0, v38
	v_add_f32_e32 v39, 1.0, v39
	v_rcp_f32_e32 v38, v38
	v_rcp_f32_e32 v39, v39
	v_mov_b32_e32 v37, v133
	v_lshl_add_u64 v[36:37], v[68:69], 0, v[36:37]
	v_lshl_add_u64 v[36:37], v[36:37], 0, v[132:133]
	v_pk_mul_f32 v[32:33], v[32:33], v[38:39]
	global_store_dwordx4 v[52:53], v[44:47], off
	v_pk_mul_f32 v[28:29], v[32:33], v[28:29]
	s_nop 0
	v_cvt_pk_bf16_f32 v28, v28, v29
	v_mul_f32_e32 v29, 0xbfb8aa3b, v34
	v_exp_f32_e32 v29, v29
	s_nop 0
	v_add_f32_e32 v29, 1.0, v29
	v_rcp_f32_e32 v32, v29
	v_mul_f32_e32 v29, 0xbfb8aa3b, v35
	v_exp_f32_e32 v29, v29
	s_nop 0
	v_add_f32_e32 v29, 1.0, v29
	v_rcp_f32_e32 v33, v29
	s_nop 0
	v_pk_mul_f32 v[32:33], v[34:35], v[32:33]
	s_nop 0
	v_pk_mul_f32 v[30:31], v[32:33], v[30:31]
	s_nop 0
	v_cvt_pk_bf16_f32 v29, v30, v31
	v_mul_f32_e32 v30, 0xbfb8aa3b, v24
	v_mul_f32_e32 v31, 0xbfb8aa3b, v25
	v_exp_f32_e32 v30, v30
	v_exp_f32_e32 v31, v31
	v_add_f32_e32 v30, 1.0, v30
	v_add_f32_e32 v31, 1.0, v31
	v_rcp_f32_e32 v30, v30
	v_rcp_f32_e32 v31, v31
	s_nop 0
	v_pk_mul_f32 v[24:25], v[24:25], v[30:31]
	s_nop 0
	v_pk_mul_f32 v[20:21], v[24:25], v[20:21]
	s_nop 0
	v_cvt_pk_bf16_f32 v30, v20, v21
	v_mul_f32_e32 v20, 0xbfb8aa3b, v26
	v_mul_f32_e32 v21, 0xbfb8aa3b, v27
	v_exp_f32_e32 v20, v20
	v_exp_f32_e32 v21, v21
	v_add_f32_e32 v20, 1.0, v20
	v_add_f32_e32 v21, 1.0, v21
	v_rcp_f32_e32 v20, v20
	v_rcp_f32_e32 v21, v21
	s_nop 0
	v_pk_mul_f32 v[20:21], v[26:27], v[20:21]
	s_nop 0
	v_pk_mul_f32 v[20:21], v[20:21], v[22:23]
	s_nop 0
	v_cvt_pk_bf16_f32 v31, v20, v21
	v_add_u32_e32 v20, 0xb0, v145
	v_lshrrev_b32_e32 v22, 3, v20
	v_lshlrev_b32_e32 v21, 6, v20
	v_and_or_b32 v22, v22, 14, s64
	v_lshlrev_b32_e32 v23, 2, v20
	v_and_or_b32 v21, v21, s15, v142
	v_lshlrev_b32_e32 v22, 10, v22
	v_and_b32_e32 v23, 32, v23
	v_bitop3_b32 v132, v21, v22, v23 bitop3:0xde
	v_mul_f32_e32 v22, 0xbfb8aa3b, v16
	v_mul_f32_e32 v23, 0xbfb8aa3b, v17
	v_exp_f32_e32 v22, v22
	v_exp_f32_e32 v23, v23
	v_lshlrev_b32_e32 v20, 7, v20
	v_and_b32_e32 v20, 0x4000, v20
	v_add_f32_e32 v22, 1.0, v22
	v_add_f32_e32 v23, 1.0, v23
	v_rcp_f32_e32 v22, v22
	v_rcp_f32_e32 v23, v23
	v_mov_b32_e32 v21, v133
	v_lshl_add_u64 v[20:21], v[68:69], 0, v[20:21]
	v_lshl_add_u64 v[20:21], v[20:21], 0, v[132:133]
	v_pk_mul_f32 v[16:17], v[16:17], v[22:23]
	global_store_dwordx4 v[36:37], v[28:31], off
	v_pk_mul_f32 v[12:13], v[16:17], v[12:13]
	s_nop 0
	v_cvt_pk_bf16_f32 v12, v12, v13
	v_mul_f32_e32 v13, 0xbfb8aa3b, v18
	v_exp_f32_e32 v13, v13
	s_nop 0
	v_add_f32_e32 v13, 1.0, v13
	v_rcp_f32_e32 v16, v13
	v_mul_f32_e32 v13, 0xbfb8aa3b, v19
	v_exp_f32_e32 v13, v13
	s_nop 0
	v_add_f32_e32 v13, 1.0, v13
	v_rcp_f32_e32 v17, v13
	s_nop 0
	v_pk_mul_f32 v[16:17], v[18:19], v[16:17]
	s_nop 0
	v_pk_mul_f32 v[14:15], v[16:17], v[14:15]
	s_nop 0
	v_cvt_pk_bf16_f32 v13, v14, v15
	v_mul_f32_e32 v14, 0xbfb8aa3b, v8
	v_mul_f32_e32 v15, 0xbfb8aa3b, v9
	v_exp_f32_e32 v14, v14
	v_exp_f32_e32 v15, v15
	v_add_f32_e32 v14, 1.0, v14
	v_add_f32_e32 v15, 1.0, v15
	v_rcp_f32_e32 v14, v14
	v_rcp_f32_e32 v15, v15
	s_nop 0
	v_pk_mul_f32 v[8:9], v[8:9], v[14:15]
	s_nop 0
	v_pk_mul_f32 v[4:5], v[8:9], v[4:5]
	s_nop 0
	v_cvt_pk_bf16_f32 v14, v4, v5
	v_mul_f32_e32 v4, 0xbfb8aa3b, v10
	v_mul_f32_e32 v5, 0xbfb8aa3b, v11
	v_exp_f32_e32 v4, v4
	v_exp_f32_e32 v5, v5
	v_add_f32_e32 v4, 1.0, v4
	v_add_f32_e32 v5, 1.0, v5
	v_rcp_f32_e32 v4, v4
	v_rcp_f32_e32 v5, v5
	s_nop 0
	v_pk_mul_f32 v[4:5], v[10:11], v[4:5]
	s_nop 0
	v_pk_mul_f32 v[4:5], v[4:5], v[6:7]
	s_nop 0
	v_cvt_pk_bf16_f32 v15, v4, v5
	global_store_dwordx4 v[20:21], v[12:15], off
	s_cbranch_vccz .LBB0_892
	s_waitcnt vmcnt(0)
	s_cmpk_gt_u32 s2, 0xff
	s_cbranch_scc1 .LBB0_903
	s_barrier
